# speedup vs baseline: 1.0499x; 1.0124x over previous
; DEV f32x4 mfma16(bf16x8 a, bf16x8 b, f32x4 c) { return __builtin_amdgcn_mfma_f32_16x16x32_bf16(a, b, c, 0, 0, 0); }
; PHASE void att_a_phase(const u16* __restrict__ GA, u16* __restrict__ OG, float* __restrict__ LSE, unsigned char* smem) {
;     ...
;   for (int bi = blockIdx.x; bi < 6144; bi += gridDim.x) {
;     const int item = bi * 4 + wid;
;     const int bh = item >> 10, sub = item & 1023;
;     const int b = bh / 12, head = bh % 12, g = head >> 2;
;     const int dsh = g * 2, d = 1 << dsh;
;     const int ntile = (S_ >> dsh) >> 4;
;     const int r = sub / ntile, jt = sub % ntile;
;     const int jq0 = jt * 16;
;     const size_t base = (size_t)b * S_;
;     bf16x8 qa[4];
;     {
;       const u16* qrow = GA + (base + (size_t)(jq0 + fr) * d + r) * 4608 + head * 128;
; #pragma unroll
;       for (int ks = 0; ks < 4; ++ks) qa[ks] = *(const bf16x8*)(qrow + ks * 32 + fq * 8);
;     }
;     f32x4 sc[9];
; #pragma unroll
;     for (int kt = 0; kt < 9; ++kt) {
;       int jk = jq0 - 128 + kt * 16 + fr;
;       int jkc = jk < 0 ? 0 : jk;
;       const u16* krow = GA + (base + (size_t)jkc * d + r) * 4608 + 1536 + head * 128;
;       f32x4 acc = {0.f, 0.f, 0.f, 0.f};
; #pragma unroll
;       for (int ks = 0; ks < 4; ++ks) {
;         bf16x8 kb = *(const bf16x8*)(krow + ks * 32 + fq * 8);
;         acc = mfma16(qa[ks], kb, acc);
;       }
;       sc[kt] = acc;
;     }
.LBB0_134:
	v_lshl_add_u32 v1, s28, 2, v192
	v_ashrrev_i32_e32 v2, 10, v1
	s_mov_b32 s0, 0x2aaaaaab
	v_mul_hi_i32 v0, v2, s0
	v_lshrrev_b32_e32 v4, 31, v0
	v_ashrrev_i32_e32 v0, 1, v0
	v_add_u32_e32 v0, v0, v4
	v_mul_lo_u32 v4, v0, 12
	v_sub_u32_e32 v48, v2, v4
	v_ashrrev_i32_e32 v2, 1, v48
	v_and_b32_e32 v204, -2, v2
	s_movk_i32 s0, 0x400
	v_lshrrev_b32_e64 v2, v204, s0
	v_add_u32_e32 v2, -1, v2
	s_movk_i32 s0, 0x3ff
	v_bitop3_b32 v58, v2, v1, s0 bitop3:0x80
	v_and_b32_e32 v3, 0x3ff, v1
	v_sub_u32_e32 v4, 10, v204
	v_lshlrev_b32_e32 v134, 4, v58
	v_ashrrev_i32_e32 v1, 31, v0
	v_lshrrev_b32_e32 v3, v4, v3
	v_lshlrev_b64 v[136:137], 14, v[0:1]
	v_or_b32_e32 v156, v134, v193
	v_lshlrev_b64 v[0:1], v204, v[156:157]
	v_or_b32_e32 v136, v136, v3
	v_lshl_add_u64 v[0:1], v[0:1], 0, v[136:137]
	v_mov_b64_e32 v[44:45], s[68:69]
	v_mad_u64_u32 v[2:3], s[0:1], v0, s75, v[44:45]
	v_mov_b32_e32 v0, v3
	v_lshlrev_b32_e32 v138, 7, v48
	v_mad_u64_u32 v[0:1], s[0:1], v1, s75, v[0:1]
	v_ashrrev_i32_e32 v139, 31, v138
	v_mov_b32_e32 v3, v0
	v_lshlrev_b64 v[140:141], 1, v[138:139]
	v_lshl_add_u64 v[0:1], v[2:3], 0, v[140:141]
	v_mov_b32_e32 v131, v157
	v_add_u32_e32 v49, 0xffffff80, v156
	v_cmp_lt_u32_e32 vcc, 7, v58
	v_lshl_add_u64 v[50:51], v[0:1], 0, v[130:131]
	global_load_dwordx4 v[20:23], v[50:51], off
	global_load_dwordx4 v[16:19], v[50:51], off offset:64
	global_load_dwordx4 v[12:15], v[50:51], off offset:128
	global_load_dwordx4 v[8:11], v[50:51], off offset:192
	v_cndmask_b32_e32 v0, 0, v49, vcc
	v_ashrrev_i32_e32 v1, 31, v0
	v_lshlrev_b64 v[0:1], v204, v[0:1]
	v_lshl_add_u64 v[0:1], v[0:1], 0, v[136:137]
	v_mad_u64_u32 v[2:3], s[0:1], v0, s75, v[44:45]
	v_mov_b32_e32 v0, v3
	v_mad_u64_u32 v[0:1], s[0:1], v1, s75, v[0:1]
	v_mov_b32_e32 v3, v0
	v_lshl_add_u64 v[0:1], v[2:3], 0, v[140:141]
	v_lshl_add_u64 v[24:25], v[0:1], 0, v[130:131]
	global_load_dwordx4 v[0:3], v[24:25], off offset:3072
	global_load_dwordx4 v[4:7], v[24:25], off offset:3136
	global_load_dwordx4 v[236:239], v[24:25], off offset:3200
	global_load_dwordx4 v[240:243], v[24:25], off offset:3264
	v_add_u32_e32 v53, v134, v196
	v_cmp_lt_u32_e64 s[0:1], 6, v58
	v_add_u32_e32 v52, v134, v197
	v_add_u32_e32 v60, v134, v198
	v_add_u32_e32 v61, v134, v199
	v_add_u32_e32 v62, v134, v200
	v_add_u32_e32 v63, v134, v201
	v_add_u32_e32 v64, v134, v202
	s_movk_i32 s29, 0x81
	s_waitcnt vmcnt(3)
	v_mfma_f32_16x16x32_bf16 v[0:3], v[20:23], v[0:3], 0
	s_waitcnt vmcnt(2)
	v_mfma_f32_16x16x32_bf16 v[0:3], v[16:19], v[4:7], v[0:3]
	s_waitcnt vmcnt(1)
	v_mfma_f32_16x16x32_bf16 v[0:3], v[12:15], v[236:239], v[0:3]
	s_waitcnt vmcnt(0)
	v_mfma_f32_16x16x32_bf16 v[0:3], v[8:11], v[240:243], v[0:3]
	v_cndmask_b32_e64 v4, 0, v53, s[0:1]
	v_ashrrev_i32_e32 v5, 31, v4
	v_lshlrev_b64 v[4:5], v204, v[4:5]
	v_lshl_add_u64 v[4:5], v[4:5], 0, v[136:137]
	v_mad_u64_u32 v[6:7], s[2:3], v4, s75, v[44:45]
	v_mov_b32_e32 v4, v7
	v_mad_u64_u32 v[4:5], s[2:3], v5, s75, v[4:5]
	v_mov_b32_e32 v7, v4
	v_lshl_add_u64 v[4:5], v[6:7], 0, v[140:141]
	v_lshl_add_u64 v[28:29], v[4:5], 0, v[130:131]
	global_load_dwordx4 v[4:7], v[28:29], off offset:3072
	global_load_dwordx4 v[24:27], v[28:29], off offset:3136
	global_load_dwordx4 v[236:239], v[28:29], off offset:3200
	global_load_dwordx4 v[240:243], v[28:29], off offset:3264
	v_cmp_lt_u32_e64 s[2:3], 5, v58
	v_mul_f32_e32 v0, 0x3db504f3, v0
	v_mul_f32_e32 v3, 0x3db504f3, v3
	s_waitcnt vmcnt(3)
	v_mfma_f32_16x16x32_bf16 v[4:7], v[20:23], v[4:7], 0
	s_waitcnt vmcnt(2)
	v_mfma_f32_16x16x32_bf16 v[4:7], v[16:19], v[24:27], v[4:7]
	s_waitcnt vmcnt(1)
	v_mfma_f32_16x16x32_bf16 v[4:7], v[12:15], v[236:239], v[4:7]
	s_waitcnt vmcnt(0)
	v_mfma_f32_16x16x32_bf16 v[4:7], v[8:11], v[240:243], v[4:7]
	v_cndmask_b32_e64 v24, 0, v52, s[2:3]
	v_ashrrev_i32_e32 v25, 31, v24
	v_lshlrev_b64 v[24:25], v204, v[24:25]
	v_lshl_add_u64 v[24:25], v[24:25], 0, v[136:137]
	v_mad_u64_u32 v[26:27], s[4:5], v24, s75, v[44:45]
	v_mov_b32_e32 v24, v27
	v_mad_u64_u32 v[24:25], s[4:5], v25, s75, v[24:25]
	v_mov_b32_e32 v27, v24
	v_lshl_add_u64 v[24:25], v[26:27], 0, v[140:141]
	v_lshl_add_u64 v[32:33], v[24:25], 0, v[130:131]
	global_load_dwordx4 v[24:27], v[32:33], off offset:3072
	global_load_dwordx4 v[28:31], v[32:33], off offset:3136
	global_load_dwordx4 v[236:239], v[32:33], off offset:3200
	global_load_dwordx4 v[240:243], v[32:33], off offset:3264
	v_cmp_lt_u32_e64 s[4:5], 4, v58
	v_mul_f32_e32 v4, 0x3db504f3, v4
	s_waitcnt vmcnt(3)
	v_mfma_f32_16x16x32_bf16 v[24:27], v[20:23], v[24:27], 0
	s_waitcnt vmcnt(2)
	v_mfma_f32_16x16x32_bf16 v[24:27], v[16:19], v[28:31], v[24:27]
	s_waitcnt vmcnt(1)
	v_mfma_f32_16x16x32_bf16 v[24:27], v[12:15], v[236:239], v[24:27]
	s_waitcnt vmcnt(0)
	v_mfma_f32_16x16x32_bf16 v[24:27], v[8:11], v[240:243], v[24:27]
	v_cndmask_b32_e64 v28, 0, v60, s[4:5]
	v_ashrrev_i32_e32 v29, 31, v28
	v_lshlrev_b64 v[28:29], v204, v[28:29]
	v_lshl_add_u64 v[28:29], v[28:29], 0, v[136:137]
	v_mad_u64_u32 v[30:31], s[10:11], v28, s75, v[44:45]
	v_mov_b32_e32 v28, v31
	v_mad_u64_u32 v[28:29], s[10:11], v29, s75, v[28:29]
	v_mov_b32_e32 v31, v28
	v_lshl_add_u64 v[28:29], v[30:31], 0, v[140:141]
	v_lshl_add_u64 v[36:37], v[28:29], 0, v[130:131]
	global_load_dwordx4 v[28:31], v[36:37], off offset:3072
	global_load_dwordx4 v[32:35], v[36:37], off offset:3136
	global_load_dwordx4 v[236:239], v[36:37], off offset:3200
	global_load_dwordx4 v[240:243], v[36:37], off offset:3264
	v_cmp_lt_u32_e64 s[10:11], 3, v58
	s_waitcnt vmcnt(3)
	v_mfma_f32_16x16x32_bf16 v[28:31], v[20:23], v[28:31], 0
	s_waitcnt vmcnt(2)
	v_mfma_f32_16x16x32_bf16 v[28:31], v[16:19], v[32:35], v[28:31]
	s_waitcnt vmcnt(1)
; DEV f32x4 mfma16(bf16x8 a, bf16x8 b, f32x4 c) { return __builtin_amdgcn_mfma_f32_16x16x32_bf16(a, b, c, 0, 0, 0); }
; PHASE void att_a_phase(const u16* __restrict__ GA, u16* __restrict__ OG, float* __restrict__ LSE, unsigned char* smem) {
;     ...
;     for (int kt = 0; kt < 9; ++kt) {
;       int jk = jq0 - 128 + kt * 16 + fr;
;       int jkc = jk < 0 ? 0 : jk;
;       const u16* krow = GA + (base + (size_t)jkc * d + r) * 4608 + 1536 + head * 128;
;       f32x4 acc = {0.f, 0.f, 0.f, 0.f};
; #pragma unroll
;       for (int ks = 0; ks < 4; ++ks) {
;         bf16x8 kb = *(const bf16x8*)(krow + ks * 32 + fq * 8);
;         acc = mfma16(qa[ks], kb, acc);
;       }
;       sc[kt] = acc;
;     }
	v_mfma_f32_16x16x32_bf16 v[28:31], v[12:15], v[236:239], v[28:31]
	s_waitcnt vmcnt(0)
	v_mfma_f32_16x16x32_bf16 v[28:31], v[8:11], v[240:243], v[28:31]
	v_cndmask_b32_e64 v32, 0, v61, s[10:11]
	v_ashrrev_i32_e32 v33, 31, v32
	v_lshlrev_b64 v[32:33], v204, v[32:33]
	v_lshl_add_u64 v[32:33], v[32:33], 0, v[136:137]
	v_mad_u64_u32 v[34:35], s[12:13], v32, s75, v[44:45]
	v_mov_b32_e32 v32, v35
	v_mad_u64_u32 v[32:33], s[12:13], v33, s75, v[32:33]
	v_mov_b32_e32 v35, v32
	v_lshl_add_u64 v[32:33], v[34:35], 0, v[140:141]
	v_lshl_add_u64 v[40:41], v[32:33], 0, v[130:131]
	global_load_dwordx4 v[32:35], v[40:41], off offset:3072
	global_load_dwordx4 v[36:39], v[40:41], off offset:3136
	global_load_dwordx4 v[236:239], v[40:41], off offset:3200
	global_load_dwordx4 v[240:243], v[40:41], off offset:3264
	v_cmp_lt_u32_e64 s[12:13], 2, v58
	s_waitcnt vmcnt(3)
	v_mfma_f32_16x16x32_bf16 v[32:35], v[20:23], v[32:35], 0
	s_waitcnt vmcnt(2)
	v_mfma_f32_16x16x32_bf16 v[32:35], v[16:19], v[36:39], v[32:35]
	s_waitcnt vmcnt(1)
	v_mfma_f32_16x16x32_bf16 v[32:35], v[12:15], v[236:239], v[32:35]
	s_waitcnt vmcnt(0)
	v_mfma_f32_16x16x32_bf16 v[32:35], v[8:11], v[240:243], v[32:35]
	v_cndmask_b32_e64 v36, 0, v62, s[12:13]
	v_ashrrev_i32_e32 v37, 31, v36
	v_lshlrev_b64 v[36:37], v204, v[36:37]
	v_lshl_add_u64 v[36:37], v[36:37], 0, v[136:137]
	v_mad_u64_u32 v[38:39], s[14:15], v36, s75, v[44:45]
	v_mov_b32_e32 v36, v39
	v_mad_u64_u32 v[36:37], s[14:15], v37, s75, v[36:37]
	v_mov_b32_e32 v39, v36
	v_lshl_add_u64 v[36:37], v[38:39], 0, v[140:141]
	v_lshl_add_u64 v[46:47], v[36:37], 0, v[130:131]
	global_load_dwordx4 v[36:39], v[46:47], off offset:3072
	global_load_dwordx4 v[40:43], v[46:47], off offset:3136
	global_load_dwordx4 v[236:239], v[46:47], off offset:3200
	global_load_dwordx4 v[240:243], v[46:47], off offset:3264
	v_cmp_lt_u32_e64 s[14:15], 1, v58
	s_waitcnt vmcnt(3)
	v_mfma_f32_16x16x32_bf16 v[36:39], v[20:23], v[36:39], 0
	s_waitcnt vmcnt(2)
	v_mfma_f32_16x16x32_bf16 v[36:39], v[16:19], v[40:43], v[36:39]
	s_waitcnt vmcnt(1)
	v_mfma_f32_16x16x32_bf16 v[36:39], v[12:15], v[236:239], v[36:39]
	s_waitcnt vmcnt(0)
	v_mfma_f32_16x16x32_bf16 v[36:39], v[8:11], v[240:243], v[36:39]
	v_cndmask_b32_e64 v40, 0, v63, s[14:15]
	v_ashrrev_i32_e32 v41, 31, v40
	v_lshlrev_b64 v[40:41], v204, v[40:41]
	v_lshl_add_u64 v[40:41], v[40:41], 0, v[136:137]
	v_mad_u64_u32 v[42:43], s[16:17], v40, s75, v[44:45]
	v_mov_b32_e32 v40, v43
	v_mad_u64_u32 v[40:41], s[16:17], v41, s75, v[40:41]
	v_mov_b32_e32 v43, v40
	v_lshl_add_u64 v[40:41], v[42:43], 0, v[140:141]
	v_lshl_add_u64 v[46:47], v[40:41], 0, v[130:131]
	global_load_dwordx4 v[40:43], v[46:47], off offset:3072
	global_load_dwordx4 v[54:57], v[46:47], off offset:3136
	v_cmp_ne_u32_e64 s[16:17], 0, v58
	s_waitcnt vmcnt(1)
	v_mfma_f32_16x16x32_bf16 v[40:43], v[20:23], v[40:43], 0
	s_waitcnt vmcnt(0)
	v_mfma_f32_16x16x32_bf16 v[40:43], v[16:19], v[54:57], v[40:43]
	global_load_dwordx4 v[54:57], v[46:47], off offset:3200
	s_waitcnt vmcnt(0)
	v_mfma_f32_16x16x32_bf16 v[40:43], v[12:15], v[54:57], v[40:43]
	global_load_dwordx4 v[54:57], v[46:47], off offset:3264
	v_cndmask_b32_e64 v46, 0, v64, s[16:17]
	v_ashrrev_i32_e32 v47, 31, v46
	v_lshlrev_b64 v[46:47], v204, v[46:47]
	v_lshl_add_u64 v[46:47], v[46:47], 0, v[136:137]
	v_mad_u64_u32 v[44:45], s[18:19], v46, s75, v[44:45]
	v_mov_b32_e32 v46, v45
	v_mad_u64_u32 v[46:47], s[18:19], v47, s75, v[46:47]
	v_mov_b32_e32 v45, v46
	v_lshl_add_u64 v[44:45], v[44:45], 0, v[140:141]
	v_lshl_add_u64 v[58:59], v[44:45], 0, v[130:131]
	global_load_dwordx4 v[44:47], v[58:59], off offset:3072
	s_waitcnt vmcnt(1)
	v_mfma_f32_16x16x32_bf16 v[40:43], v[8:11], v[54:57], v[40:43]
	global_load_dwordx4 v[54:57], v[58:59], off offset:3136
	s_waitcnt vmcnt(1)
	v_mfma_f32_16x16x32_bf16 v[44:47], v[20:23], v[44:47], 0
	s_waitcnt vmcnt(0)
	v_mfma_f32_16x16x32_bf16 v[44:47], v[16:19], v[54:57], v[44:47]
	global_load_dwordx4 v[54:57], v[58:59], off offset:3200
	s_waitcnt vmcnt(0)
	v_mfma_f32_16x16x32_bf16 v[44:47], v[12:15], v[54:57], v[44:47]
	global_load_dwordx4 v[54:57], v[58:59], off offset:3264
	s_waitcnt vmcnt(0)
	v_mfma_f32_16x16x32_bf16 v[44:47], v[8:11], v[54:57], v[44:47]
	global_load_dwordx4 v[54:57], v[50:51], off offset:3072
	s_waitcnt vmcnt(0)
	v_mfma_f32_16x16x32_bf16 v[20:23], v[20:23], v[54:57], 0
	global_load_dwordx4 v[54:57], v[50:51], off offset:3136
	s_waitcnt vmcnt(0)
	v_mfma_f32_16x16x32_bf16 v[16:19], v[16:19], v[54:57], v[20:23]
	s_nop 4
	global_load_dwordx4 v[20:23], v[50:51], off offset:3200
	s_waitcnt vmcnt(0)
	v_mfma_f32_16x16x32_bf16 v[12:15], v[12:15], v[20:23], v[16:19]
	s_nop 2
	global_load_dwordx4 v[16:19], v[50:51], off offset:3264
	v_cndmask_b32_e64 v20, v185, v4, s[0:1]
	s_waitcnt vmcnt(0)
; PHASE void att_a_phase(const u16* __restrict__ GA, u16* __restrict__ OG, float* __restrict__ LSE, unsigned char* smem) {
;     ...
;     float mx[4] = {-1e30f, -1e30f, -1e30f, -1e30f};
; #pragma unroll
;     for (int kt = 0; kt < 9; ++kt) {
;       int jk = jq0 - 128 + kt * 16 + fr;
; #pragma unroll
;       for (int j = 0; j < 4; ++j) {
;         int jq = jq0 + fq * 4 + j;
;         bool valid = (jk >= 0) && (jk <= jq) && (jq - jk <= 128);
;         float v = valid ? sc[kt][j] * scale : -1e30f;
;         sc[kt][j] = v;
;         mx[j] = fmaxf(mx[j], v);
;       }
;     }
	v_mfma_f32_16x16x32_bf16 v[8:11], v[8:11], v[16:19], v[12:15]
	v_or_b32_e32 v16, v134, v195
	v_cmp_ge_i32_e64 s[18:19], v16, v49
	s_nop 0
	v_sub_u32_e32 v12, v16, v49
	s_and_b64 s[34:35], vcc, s[18:19]
	v_cmp_gt_i32_e64 s[18:19], s29, v12
	s_and_b64 s[18:19], s[34:35], s[18:19]
	v_or_b32_e32 v14, 1, v16
	v_cndmask_b32_e64 v15, v185, v0, s[18:19]
	v_cmp_ge_i32_e64 s[18:19], v14, v49
	v_sub_u32_e32 v0, v14, v49
	s_and_b64 s[34:35], vcc, s[18:19]
	v_cmp_gt_i32_e64 s[18:19], s29, v0
	s_and_b64 s[18:19], s[34:35], s[18:19]
	v_mul_f32_e32 v0, 0x3db504f3, v1
	v_or_b32_e32 v12, 2, v16
	v_cndmask_b32_e64 v17, v185, v0, s[18:19]
	v_cmp_ge_i32_e64 s[18:19], v12, v49
	v_sub_u32_e32 v0, v12, v49
	s_and_b64 s[34:35], vcc, s[18:19]
	v_cmp_gt_i32_e64 s[18:19], s29, v0
	s_and_b64 s[18:19], s[34:35], s[18:19]
	v_mul_f32_e32 v0, 0x3db504f3, v2
	v_cndmask_b32_e64 v18, v185, v0, s[18:19]
	v_or_b32_e32 v0, 3, v16
	v_cmp_ge_i32_e64 s[18:19], v0, v49
	v_sub_u32_e32 v19, v0, v49
	s_and_b64 s[18:19], vcc, s[18:19]
	v_cmp_gt_i32_e32 vcc, s29, v19
	s_and_b64 vcc, s[18:19], vcc
	v_sub_u32_e32 v4, v14, v53
	v_cndmask_b32_e32 v19, v185, v3, vcc
	v_cmp_ge_i32_e32 vcc, v14, v53
	s_and_b64 s[18:19], s[0:1], vcc
	v_cmp_gt_i32_e32 vcc, s29, v4
	s_and_b64 vcc, s[18:19], vcc
	v_mul_f32_e32 v4, 0x3db504f3, v5
	v_cndmask_b32_e32 v21, v185, v4, vcc
	v_cmp_ge_i32_e32 vcc, v12, v53
	v_sub_u32_e32 v4, v12, v53
	s_and_b64 s[18:19], s[0:1], vcc
	v_cmp_gt_i32_e32 vcc, s29, v4
	s_and_b64 vcc, s[18:19], vcc
	v_mul_f32_e32 v4, 0x3db504f3, v6
	v_cndmask_b32_e32 v22, v185, v4, vcc
	v_cmp_ge_i32_e32 vcc, v0, v53
	v_sub_u32_e32 v4, v0, v53
	s_and_b64 s[0:1], s[0:1], vcc
	v_cmp_gt_i32_e32 vcc, s29, v4
	s_and_b64 vcc, s[0:1], vcc
	v_mul_f32_e32 v4, 0x3db504f3, v7
	v_cndmask_b32_e32 v49, v185, v4, vcc
	v_cmp_ge_i32_e32 vcc, v14, v52
	v_sub_u32_e32 v5, v14, v52
	s_and_b64 s[0:1], s[2:3], vcc
	v_cmp_gt_i32_e32 vcc, s29, v5
	s_and_b64 vcc, s[0:1], vcc
	v_mul_f32_e32 v5, 0x3db504f3, v25
	v_mul_f32_e32 v4, 0x3db504f3, v24
	v_cndmask_b32_e32 v24, v185, v5, vcc
	v_cmp_ge_i32_e32 vcc, v12, v52
	v_sub_u32_e32 v5, v12, v52
	s_and_b64 s[0:1], s[2:3], vcc
	v_cmp_gt_i32_e32 vcc, s29, v5
	s_and_b64 vcc, s[0:1], vcc
	v_mul_f32_e32 v5, 0x3db504f3, v26
	v_cndmask_b32_e32 v25, v185, v5, vcc
	v_cmp_ge_i32_e32 vcc, v0, v52
	v_sub_u32_e32 v5, v0, v52
	s_and_b64 s[0:1], s[2:3], vcc
	v_cmp_gt_i32_e32 vcc, s29, v5
	s_and_b64 vcc, s[0:1], vcc
	v_mul_f32_e32 v5, 0x3db504f3, v27
	v_cndmask_b32_e32 v26, v185, v5, vcc
	v_mul_f32_e32 v5, 0x3db504f3, v28
	v_cndmask_b32_e64 v27, v185, v5, s[4:5]
	v_cmp_ge_i32_e32 vcc, v14, v60
	v_sub_u32_e32 v5, v14, v60
	s_and_b64 s[0:1], s[4:5], vcc
	v_cmp_gt_i32_e32 vcc, s29, v5
	s_and_b64 vcc, s[0:1], vcc
	v_mul_f32_e32 v5, 0x3db504f3, v29
	v_cndmask_b32_e32 v50, v185, v5, vcc
	v_cmp_ge_i32_e32 vcc, v12, v60
	v_sub_u32_e32 v5, v12, v60
	s_and_b64 s[0:1], s[4:5], vcc
	v_cmp_gt_i32_e32 vcc, s29, v5
	s_and_b64 vcc, s[0:1], vcc
	v_mul_f32_e32 v5, 0x3db504f3, v30
	v_cndmask_b32_e32 v29, v185, v5, vcc
	v_cmp_ge_i32_e32 vcc, v0, v60
	v_sub_u32_e32 v5, v0, v60
	s_and_b64 s[0:1], s[4:5], vcc
	v_cmp_gt_i32_e32 vcc, s29, v5
	s_and_b64 vcc, s[0:1], vcc
	v_mul_f32_e32 v5, 0x3db504f3, v31
	v_cndmask_b32_e32 v31, v185, v5, vcc
	v_mul_f32_e32 v5, 0x3db504f3, v32
	v_cndmask_b32_e64 v28, v185, v5, s[10:11]
	v_cmp_ge_i32_e32 vcc, v14, v61
	v_sub_u32_e32 v5, v14, v61
	s_and_b64 s[0:1], s[10:11], vcc
	v_cmp_gt_i32_e32 vcc, s29, v5
	s_and_b64 vcc, s[0:1], vcc
	v_mul_f32_e32 v5, 0x3db504f3, v33
	v_cndmask_b32_e32 v30, v185, v5, vcc
	v_cmp_ge_i32_e32 vcc, v12, v61
	v_sub_u32_e32 v5, v12, v61
	s_and_b64 s[0:1], s[10:11], vcc
	v_cmp_gt_i32_e32 vcc, s29, v5
	s_and_b64 vcc, s[0:1], vcc
	v_mul_f32_e32 v5, 0x3db504f3, v34
	v_cndmask_b32_e32 v32, v185, v5, vcc
	v_cmp_ge_i32_e32 vcc, v0, v61
	v_sub_u32_e32 v5, v0, v61
	s_and_b64 s[0:1], s[10:11], vcc
	v_cmp_gt_i32_e32 vcc, s29, v5
	s_and_b64 vcc, s[0:1], vcc
	v_mul_f32_e32 v5, 0x3db504f3, v35
	v_cndmask_b32_e32 v33, v185, v5, vcc
	v_mul_f32_e32 v5, 0x3db504f3, v36
	v_cndmask_b32_e64 v34, v185, v5, s[12:13]
	v_cmp_ge_i32_e32 vcc, v14, v62
	v_sub_u32_e32 v5, v14, v62
	s_and_b64 s[0:1], s[12:13], vcc
	v_cmp_gt_i32_e32 vcc, s29, v5
	s_and_b64 vcc, s[0:1], vcc
	v_mul_f32_e32 v5, 0x3db504f3, v37
	v_cndmask_b32_e32 v35, v185, v5, vcc
	v_cmp_ge_i32_e32 vcc, v12, v62
	v_sub_u32_e32 v5, v12, v62
	s_and_b64 s[0:1], s[12:13], vcc
	v_cmp_gt_i32_e32 vcc, s29, v5
	s_and_b64 vcc, s[0:1], vcc
	v_mul_f32_e32 v5, 0x3db504f3, v38
	v_cndmask_b32_e32 v36, v185, v5, vcc
	v_cmp_ge_i32_e32 vcc, v0, v62
	v_sub_u32_e32 v5, v0, v62
	s_and_b64 s[0:1], s[12:13], vcc
	v_cmp_gt_i32_e32 vcc, s29, v5
	s_and_b64 vcc, s[0:1], vcc
	v_mul_f32_e32 v5, 0x3db504f3, v39
	v_cndmask_b32_e32 v38, v185, v5, vcc
	v_mul_f32_e32 v5, 0x3db504f3, v40
	v_cndmask_b32_e64 v37, v185, v5, s[14:15]
	v_cmp_ge_i32_e32 vcc, v14, v63
	v_sub_u32_e32 v5, v14, v63
	s_and_b64 s[0:1], s[14:15], vcc
	v_cmp_gt_i32_e32 vcc, s29, v5
	s_and_b64 vcc, s[0:1], vcc
	v_mul_f32_e32 v5, 0x3db504f3, v41
	v_cndmask_b32_e32 v39, v185, v5, vcc
	v_cmp_ge_i32_e32 vcc, v12, v63
	v_sub_u32_e32 v5, v12, v63
	s_and_b64 s[0:1], s[14:15], vcc
	v_cmp_gt_i32_e32 vcc, s29, v5
	s_and_b64 vcc, s[0:1], vcc
	v_mul_f32_e32 v5, 0x3db504f3, v42
	v_cndmask_b32_e32 v40, v185, v5, vcc
	v_cmp_ge_i32_e32 vcc, v0, v63
	v_sub_u32_e32 v5, v0, v63
	s_and_b64 s[0:1], s[14:15], vcc
	v_cmp_gt_i32_e32 vcc, s29, v5
	s_and_b64 vcc, s[0:1], vcc
	v_mul_f32_e32 v5, 0x3db504f3, v43
	v_cndmask_b32_e32 v41, v185, v5, vcc
	v_mul_f32_e32 v5, 0x3db504f3, v44
	v_cndmask_b32_e64 v42, v185, v5, s[16:17]
	v_cmp_ge_i32_e32 vcc, v14, v64
	v_sub_u32_e32 v5, v14, v64
	s_and_b64 s[0:1], s[16:17], vcc
; DEV int shx(int v, int o) { return __builtin_amdgcn_ds_bpermute((LANE_() ^ o) << 2, v); }
; DEV float shx(float v, int o) { return __int_as_float(__builtin_amdgcn_ds_bpermute((LANE_() ^ o) << 2, __float_as_int(v))); }
; DEV float grp16_max(float v) {
; #pragma unroll
;   for (int o = 8; o > 0; o >>= 1) v = fmaxf(v, shx(v, o));
;   return v;
; }
; PHASE void att_a_phase(const u16* __restrict__ GA, u16* __restrict__ OG, float* __restrict__ LSE, unsigned char* smem) {
;     ...
;     float mx[4] = {-1e30f, -1e30f, -1e30f, -1e30f};
; #pragma unroll
;     for (int kt = 0; kt < 9; ++kt) {
;       int jk = jq0 - 128 + kt * 16 + fr;
; #pragma unroll
;       for (int j = 0; j < 4; ++j) {
;         int jq = jq0 + fq * 4 + j;
;         bool valid = (jk >= 0) && (jk <= jq) && (jq - jk <= 128);
;         float v = valid ? sc[kt][j] * scale : -1e30f;
;         sc[kt][j] = v;
;         mx[j] = fmaxf(mx[j], v);
;       }
;     }
;     float l[4] = {0.f, 0.f, 0.f, 0.f};
; #pragma unroll
;     for (int j = 0; j < 4; ++j) mx[j] = grp16_max(mx[j]);
; #pragma unroll
;     for (int kt = 0; kt < 9; ++kt)
; #pragma unroll
;       for (int j = 0; j < 4; ++j) {
;         float e = __expf(sc[kt][j] - mx[j]);
;         sc[kt][j] = e;
;         l[j] += e;
;       }
	v_cmp_gt_i32_e32 vcc, s29, v5
	s_and_b64 vcc, s[0:1], vcc
	v_mul_f32_e32 v5, 0x3db504f3, v45
	v_cndmask_b32_e32 v43, v185, v5, vcc
	v_cmp_ge_i32_e32 vcc, v12, v64
	v_sub_u32_e32 v5, v12, v64
	s_and_b64 s[0:1], s[16:17], vcc
	v_cmp_gt_i32_e32 vcc, s29, v5
	s_and_b64 vcc, s[0:1], vcc
	v_mul_f32_e32 v5, 0x3db504f3, v46
	v_cndmask_b32_e32 v46, v185, v5, vcc
	v_cmp_ge_i32_e32 vcc, v0, v64
	v_sub_u32_e32 v5, v0, v64
	s_and_b64 s[0:1], s[16:17], vcc
	v_cmp_gt_i32_e32 vcc, s29, v5
	s_and_b64 vcc, s[0:1], vcc
	v_mul_f32_e32 v5, 0x3db504f3, v47
	v_cndmask_b32_e32 v51, v185, v5, vcc
	v_mul_f32_e32 v5, 0x3db504f3, v8
	v_max_f32_e32 v1, 0xf149f2ca, v17
	v_cndmask_b32_e64 v47, v5, v185, s[8:9]
	v_sub_u32_e32 v5, v14, v156
	v_max3_f32 v1, v1, v21, v24
	v_cmp_ge_u32_e32 vcc, v14, v156
	v_cmp_gt_i32_e64 s[0:1], s29, v5
	v_max3_f32 v1, v1, v50, v30
	s_and_b64 vcc, vcc, s[0:1]
	v_mul_f32_e32 v5, 0x3db504f3, v9
	v_max3_f32 v1, v1, v35, v39
	v_cndmask_b32_e32 v54, v185, v5, vcc
	v_max3_f32 v5, v1, v43, v54
	v_sub_u32_e32 v1, v12, v156
	v_cmp_ge_u32_e32 vcc, v12, v156
	v_cmp_gt_i32_e64 s[0:1], s29, v1
	s_and_b64 vcc, vcc, s[0:1]
	v_mul_f32_e32 v1, 0x3db504f3, v10
	v_cndmask_b32_e32 v55, v185, v1, vcc
	v_sub_u32_e32 v1, v0, v156
	v_cmp_ge_u32_e32 vcc, v0, v156
	v_cmp_gt_i32_e64 s[0:1], s29, v1
	v_max_f32_e32 v13, 0xf149f2ca, v15
	v_cndmask_b32_e64 v23, v185, v4, s[2:3]
	s_and_b64 vcc, vcc, s[0:1]
	v_mul_f32_e32 v1, 0x3db504f3, v11
	v_max3_f32 v4, v13, v20, v23
	v_cndmask_b32_e32 v56, v185, v1, vcc
	v_mov_b32_e32 v1, v184
	v_max3_f32 v4, v4, v27, v28
	v_max3_f32 v4, v4, v34, v37
	v_lshlrev_b32_e32 v1, 2, v1
	v_max3_f32 v4, v4, v42, v47
	v_xor_b32_e32 v1, 32, v1
	ds_bpermute_b32 v1, v1, v4
	v_max_f32_e32 v2, 0xf149f2ca, v18
	v_max3_f32 v2, v2, v22, v25
	v_max3_f32 v2, v2, v29, v32
	v_max3_f32 v2, v2, v36, v40
	s_waitcnt lgkmcnt(0)
	v_max_f32_e32 v1, v1, v1
	v_max_f32_e32 v1, v4, v1
	v_mov_b32_e32 v4, v184
	v_max3_f32 v2, v2, v46, v55
	v_lshlrev_b32_e32 v4, 2, v4
	v_xor_b32_e32 v4, 16, v4
	ds_bpermute_b32 v4, v4, v1
	v_max_f32_e32 v3, 0xf149f2ca, v19
	v_max3_f32 v3, v3, v49, v26
	v_max3_f32 v3, v3, v31, v33
	v_max3_f32 v3, v3, v38, v41
	s_waitcnt lgkmcnt(0)
	v_max_f32_e32 v4, v4, v4
	v_max_f32_e32 v1, v1, v4
	v_mov_b32_e32 v4, v184
	v_max3_f32 v3, v3, v51, v56
	v_lshlrev_b32_e32 v4, 2, v4
	v_xor_b32_e32 v4, 8, v4
	ds_bpermute_b32 v4, v4, v1
	s_waitcnt lgkmcnt(0)
	v_max_f32_e32 v4, v4, v4
	v_max_f32_e32 v1, v1, v4
	v_mov_b32_e32 v4, v184
	s_nop 0
	v_lshlrev_b32_e32 v4, 2, v4
	v_xor_b32_e32 v4, 4, v4
	ds_bpermute_b32 v4, v4, v1
	s_waitcnt lgkmcnt(0)
	v_max_f32_e32 v4, v4, v4
	v_max_f32_e32 v1, v1, v4
	v_mov_b32_e32 v4, v184
	v_sub_f32_e32 v6, v20, v1
	v_lshlrev_b32_e32 v4, 2, v4
	v_xor_b32_e32 v4, 32, v4
	ds_bpermute_b32 v4, v4, v5
	v_mul_f32_e32 v6, 0x3fb8aa3b, v6
	v_sub_f32_e32 v10, v23, v1
	v_exp_f32_e32 v6, v6
	v_mul_f32_e32 v10, 0x3fb8aa3b, v10
	s_waitcnt lgkmcnt(0)
	v_max_f32_e32 v4, v4, v4
	v_max_f32_e32 v4, v5, v4
	v_mov_b32_e32 v5, v184
	v_exp_f32_e32 v10, v10
	v_lshlrev_b32_e32 v5, 2, v5
	v_xor_b32_e32 v5, 16, v5
	ds_bpermute_b32 v5, v5, v4
	s_waitcnt lgkmcnt(0)
	v_max_f32_e32 v5, v5, v5
	v_max_f32_e32 v4, v4, v5
	v_mov_b32_e32 v5, v184
	s_nop 0
	v_lshlrev_b32_e32 v5, 2, v5
	v_xor_b32_e32 v5, 8, v5
	ds_bpermute_b32 v5, v5, v4
	s_waitcnt lgkmcnt(0)
	v_max_f32_e32 v5, v5, v5
	v_max_f32_e32 v4, v4, v5
	v_mov_b32_e32 v5, v184
	s_nop 0
	v_lshlrev_b32_e32 v5, 2, v5
	v_xor_b32_e32 v5, 4, v5
	ds_bpermute_b32 v5, v5, v4
	s_waitcnt lgkmcnt(0)
	v_max_f32_e32 v5, v5, v5
	v_max_f32_e32 v13, v4, v5
	v_mov_b32_e32 v4, v184
	v_sub_f32_e32 v7, v21, v13
	v_lshlrev_b32_e32 v4, 2, v4
	v_xor_b32_e32 v4, 32, v4
	ds_bpermute_b32 v4, v4, v2
	v_mul_f32_e32 v7, 0x3fb8aa3b, v7
	v_sub_f32_e32 v11, v24, v13
	v_exp_f32_e32 v7, v7
	v_mul_f32_e32 v11, 0x3fb8aa3b, v11
	s_waitcnt lgkmcnt(0)
	v_max_f32_e32 v4, v4, v4
	v_max_f32_e32 v2, v2, v4
	v_mov_b32_e32 v4, v184
	v_exp_f32_e32 v11, v11
	v_lshlrev_b32_e32 v4, 2, v4
	v_xor_b32_e32 v4, 16, v4
	ds_bpermute_b32 v4, v4, v2
	s_waitcnt lgkmcnt(0)
	v_max_f32_e32 v4, v4, v4
	v_max_f32_e32 v2, v2, v4
	v_mov_b32_e32 v4, v184
	s_nop 0
	v_lshlrev_b32_e32 v4, 2, v4
	v_xor_b32_e32 v4, 8, v4
	ds_bpermute_b32 v4, v4, v2
	s_waitcnt lgkmcnt(0)
	v_max_f32_e32 v4, v4, v4
	v_max_f32_e32 v2, v2, v4
	v_mov_b32_e32 v4, v184
	s_nop 0
	v_lshlrev_b32_e32 v4, 2, v4
	v_xor_b32_e32 v4, 4, v4
	ds_bpermute_b32 v4, v4, v2
	s_waitcnt lgkmcnt(0)
	v_max_f32_e32 v4, v4, v4
	v_max_f32_e32 v52, v2, v4
	v_mov_b32_e32 v2, v184
	v_sub_f32_e32 v4, v18, v52
	v_lshlrev_b32_e32 v2, 2, v2
	v_xor_b32_e32 v2, 32, v2
	ds_bpermute_b32 v2, v2, v3
	v_sub_f32_e32 v8, v22, v52
	v_mul_f32_e32 v4, 0x3fb8aa3b, v4
	v_exp_f32_e32 v4, v4
	v_mul_f32_e32 v8, 0x3fb8aa3b, v8
	s_waitcnt lgkmcnt(0)
	v_max_f32_e32 v2, v2, v2
	v_max_f32_e32 v2, v3, v2
	v_mov_b32_e32 v3, v184
	v_exp_f32_e32 v8, v8
	v_lshlrev_b32_e32 v3, 2, v3
	v_xor_b32_e32 v3, 16, v3
	ds_bpermute_b32 v3, v3, v2
	s_waitcnt lgkmcnt(0)
	v_max_f32_e32 v3, v3, v3
	v_max_f32_e32 v2, v2, v3
	v_mov_b32_e32 v3, v184
	s_nop 0
	v_lshlrev_b32_e32 v3, 2, v3
	v_xor_b32_e32 v3, 8, v3
	ds_bpermute_b32 v3, v3, v2
	s_waitcnt lgkmcnt(0)
	v_max_f32_e32 v3, v3, v3
	v_max_f32_e32 v2, v2, v3
	v_mov_b32_e32 v3, v184
	s_nop 0
	v_lshlrev_b32_e32 v3, 2, v3
	v_xor_b32_e32 v3, 4, v3
	ds_bpermute_b32 v3, v3, v2
	s_waitcnt lgkmcnt(0)
; PHASE void att_a_phase(const u16* __restrict__ GA, u16* __restrict__ OG, float* __restrict__ LSE, unsigned char* smem) {
;     ...
;     float l[4] = {0.f, 0.f, 0.f, 0.f};
; #pragma unroll
;     for (int j = 0; j < 4; ++j) mx[j] = grp16_max(mx[j]);
; #pragma unroll
;     for (int kt = 0; kt < 9; ++kt)
; #pragma unroll
;       for (int j = 0; j < 4; ++j) {
;         float e = __expf(sc[kt][j] - mx[j]);
;         sc[kt][j] = e;
;         l[j] += e;
;       }
;     float inv[4];
; #pragma unroll
;     for (int j = 0; j < 4; ++j) {
;       l[j] = grp16_sum(l[j]);
;       inv[j] = 1.f / l[j];
;     }
;     __syncthreads();
	v_max_f32_e32 v3, v3, v3
	v_max_f32_e32 v53, v2, v3
	v_sub_f32_e32 v2, v15, v1
	v_sub_f32_e32 v15, v25, v52
	v_mul_f32_e32 v15, 0x3fb8aa3b, v15
	v_exp_f32_e32 v18, v15
	v_sub_f32_e32 v15, v26, v53
	v_sub_f32_e32 v3, v17, v13
	v_mul_f32_e32 v15, 0x3fb8aa3b, v15
	v_mul_f32_e32 v2, 0x3fb8aa3b, v2
	v_mul_f32_e32 v3, 0x3fb8aa3b, v3
	v_sub_f32_e32 v5, v19, v53
	v_exp_f32_e32 v19, v15
	v_sub_f32_e32 v15, v27, v1
	v_exp_f32_e32 v2, v2
	v_exp_f32_e32 v3, v3
	v_mul_f32_e32 v15, 0x3fb8aa3b, v15
	v_exp_f32_e32 v20, v15
	v_sub_f32_e32 v15, v50, v13
	v_mul_f32_e32 v15, 0x3fb8aa3b, v15
	v_exp_f32_e32 v21, v15
	v_pk_add_f32 v[22:23], v[2:3], 0 op_sel_hi:[1,0]
	v_mul_f32_e32 v5, 0x3fb8aa3b, v5
	v_sub_f32_e32 v9, v49, v53
	v_pk_add_f32 v[22:23], v[6:7], v[22:23]
	v_sub_f32_e32 v15, v29, v52
	v_exp_f32_e32 v5, v5
	v_mul_f32_e32 v9, 0x3fb8aa3b, v9
	v_pk_add_f32 v[22:23], v[10:11], v[22:23]
	v_mul_f32_e32 v15, 0x3fb8aa3b, v15
	v_exp_f32_e32 v9, v9
	v_pk_add_f32 v[58:59], v[20:21], v[22:23]
	v_exp_f32_e32 v22, v15
	v_sub_f32_e32 v15, v31, v53
	v_mul_f32_e32 v15, 0x3fb8aa3b, v15
	v_exp_f32_e32 v23, v15
	v_pk_add_f32 v[24:25], v[4:5], 0 op_sel_hi:[1,0]
	v_sub_f32_e32 v15, v28, v1
	v_pk_add_f32 v[24:25], v[8:9], v[24:25]
	v_mul_f32_e32 v15, 0x3fb8aa3b, v15
	v_pk_add_f32 v[24:25], v[18:19], v[24:25]
	v_mov_b32_e32 v17, v184
	v_pk_add_f32 v[44:45], v[22:23], v[24:25]
	v_exp_f32_e32 v24, v15
	v_sub_f32_e32 v15, v30, v13
	v_mul_f32_e32 v15, 0x3fb8aa3b, v15
	v_exp_f32_e32 v25, v15
	v_sub_f32_e32 v15, v32, v52
	v_mul_f32_e32 v15, 0x3fb8aa3b, v15
	v_exp_f32_e32 v26, v15
	v_sub_f32_e32 v15, v33, v53
	v_mul_f32_e32 v15, 0x3fb8aa3b, v15
	v_exp_f32_e32 v27, v15
	v_sub_f32_e32 v15, v34, v1
	v_mul_f32_e32 v15, 0x3fb8aa3b, v15
	v_exp_f32_e32 v28, v15
	v_sub_f32_e32 v15, v35, v13
	v_mul_f32_e32 v15, 0x3fb8aa3b, v15
	v_exp_f32_e32 v29, v15
	v_sub_f32_e32 v15, v36, v52
	v_mul_f32_e32 v15, 0x3fb8aa3b, v15
	v_exp_f32_e32 v30, v15
	v_sub_f32_e32 v15, v38, v53
	v_mul_f32_e32 v15, 0x3fb8aa3b, v15
	v_exp_f32_e32 v31, v15
	v_sub_f32_e32 v15, v37, v1
	v_mul_f32_e32 v15, 0x3fb8aa3b, v15
	v_exp_f32_e32 v32, v15
	v_sub_f32_e32 v15, v39, v13
	v_mul_f32_e32 v15, 0x3fb8aa3b, v15
	v_exp_f32_e32 v33, v15
	v_sub_f32_e32 v15, v40, v52
	v_mul_f32_e32 v15, 0x3fb8aa3b, v15
	v_exp_f32_e32 v34, v15
	v_sub_f32_e32 v15, v41, v53
	v_mul_f32_e32 v15, 0x3fb8aa3b, v15
	v_exp_f32_e32 v35, v15
	v_sub_f32_e32 v15, v42, v1
	v_mul_f32_e32 v15, 0x3fb8aa3b, v15
	v_exp_f32_e32 v36, v15
	v_sub_f32_e32 v15, v43, v13
	v_mul_f32_e32 v15, 0x3fb8aa3b, v15
	v_exp_f32_e32 v37, v15
	v_sub_f32_e32 v15, v46, v52
	v_mul_f32_e32 v15, 0x3fb8aa3b, v15
	v_exp_f32_e32 v38, v15
	v_sub_f32_e32 v15, v51, v53
	v_mul_f32_e32 v15, 0x3fb8aa3b, v15
	v_exp_f32_e32 v39, v15
	v_sub_f32_e32 v15, v47, v1
	v_mul_f32_e32 v15, 0x3fb8aa3b, v15
	v_exp_f32_e32 v40, v15
	v_sub_f32_e32 v15, v54, v13
	v_mul_f32_e32 v15, 0x3fb8aa3b, v15
	v_exp_f32_e32 v41, v15
	v_sub_f32_e32 v15, v55, v52
	v_mul_f32_e32 v15, 0x3fb8aa3b, v15
	v_exp_f32_e32 v42, v15
	v_sub_f32_e32 v15, v56, v53
	v_mul_f32_e32 v15, 0x3fb8aa3b, v15
	v_exp_f32_e32 v43, v15
	v_mov_b32_e32 v15, v184
	v_mov_b32_e32 v46, v184
	v_pk_add_f32 v[44:45], v[26:27], v[44:45]
	v_lshlrev_b32_e32 v46, 2, v46
	v_xor_b32_e32 v49, 8, v46
	v_mov_b32_e32 v46, v184
	v_lshlrev_b32_e32 v15, 2, v15
	v_lshlrev_b32_e32 v46, 2, v46
	v_xor_b32_e32 v54, 4, v46
	v_mov_b32_e32 v46, v184
	v_xor_b32_e32 v15, 32, v15
	v_lshlrev_b32_e32 v46, 2, v46
	v_xor_b32_e32 v51, 32, v46
	v_mov_b32_e32 v46, v184
	v_lshlrev_b32_e32 v17, 2, v17
	v_lshlrev_b32_e32 v46, 2, v46
	v_xor_b32_e32 v55, 16, v46
	v_mov_b32_e32 v46, v184
	v_xor_b32_e32 v17, 16, v17
	v_lshlrev_b32_e32 v46, 2, v46
	v_xor_b32_e32 v56, 8, v46
	v_mov_b32_e32 v46, v184
	v_pk_add_f32 v[44:45], v[30:31], v[44:45]
	v_lshlrev_b32_e32 v46, 2, v46
	v_xor_b32_e32 v57, 4, v46
	v_mov_b32_e32 v46, v184
	v_pk_add_f32 v[44:45], v[34:35], v[44:45]
	v_lshlrev_b32_e32 v46, 2, v46
	v_xor_b32_e32 v60, 32, v46
	v_mov_b32_e32 v46, v184
	v_pk_add_f32 v[44:45], v[38:39], v[44:45]
	v_lshlrev_b32_e32 v46, 2, v46
	v_xor_b32_e32 v61, 16, v46
	v_mov_b32_e32 v46, v184
	v_pk_add_f32 v[44:45], v[42:43], v[44:45]
	v_lshlrev_b32_e32 v46, 2, v46
	v_xor_b32_e32 v62, 8, v46
	v_mov_b32_e32 v46, v184
	s_nop 0
	v_lshlrev_b32_e32 v46, 2, v46
	v_xor_b32_e32 v63, 4, v46
	v_mov_b32_e32 v46, v184
	s_nop 0
	v_lshlrev_b32_e32 v46, 2, v46
	v_xor_b32_e32 v64, 32, v46
	v_mov_b32_e32 v46, v184
	s_nop 0
	v_lshlrev_b32_e32 v46, 2, v46
	v_xor_b32_e32 v65, 16, v46
	v_mov_b32_e32 v46, v184
	s_nop 0
	v_lshlrev_b32_e32 v46, 2, v46
	v_xor_b32_e32 v66, 8, v46
	v_mov_b32_e32 v46, v184
	s_nop 0
	v_lshlrev_b32_e32 v46, 2, v46
	v_xor_b32_e32 v67, 4, v46
	v_pk_add_f32 v[46:47], v[24:25], v[58:59]
	s_barrier
; PHASE void att_a_phase(const u16* __restrict__ GA, u16* __restrict__ OG, float* __restrict__ LSE, unsigned char* smem) {
;     ...
;     float inv[4];
; #pragma unroll
;     for (int j = 0; j < 4; ++j) {
;       l[j] = grp16_sum(l[j]);
;       inv[j] = 1.f / l[j];
;     }
;     __syncthreads();
; #pragma unroll
;     for (int kt = 0; kt < 9; ++kt) {
;       f32x4 pv = {sc[kt][0] * inv[0], sc[kt][1] * inv[1], sc[kt][2] * inv[2], sc[kt][3] * inv[3]};
;       *(f32x4*)(Pl + (kt * 16 + fr) * 16 + fq * 4) = pv;
;     }
;     if (fr == 0) {
; #pragma unroll
;       for (int j = 0; j < 4; ++j)
;         LSE[(base + (size_t)(jq0 + fq * 4 + j) * d + r) * 12 + head] = mx[j] + __logf(l[j]);
;     }
	v_pk_add_f32 v[46:47], v[28:29], v[46:47]
	s_nop 0
	v_pk_add_f32 v[46:47], v[32:33], v[46:47]
	s_nop 0
	v_pk_add_f32 v[46:47], v[36:37], v[46:47]
	s_nop 0
	v_pk_add_f32 v[46:47], v[40:41], v[46:47]
	ds_bpermute_b32 v50, v15, v46
	ds_bpermute_b32 v51, v51, v47
	s_waitcnt lgkmcnt(0)
	v_pk_add_f32 v[46:47], v[46:47], v[50:51]
	ds_bpermute_b32 v50, v17, v46
	ds_bpermute_b32 v51, v55, v47
	ds_bpermute_b32 v55, v64, v45
	s_waitcnt lgkmcnt(1)
	v_pk_add_f32 v[46:47], v[46:47], v[50:51]
	ds_bpermute_b32 v50, v49, v46
	ds_bpermute_b32 v51, v56, v47
	s_waitcnt lgkmcnt(0)
	v_pk_add_f32 v[46:47], v[46:47], v[50:51]
	ds_bpermute_b32 v50, v54, v46
	ds_bpermute_b32 v51, v57, v47
	s_waitcnt lgkmcnt(0)
	v_pk_add_f32 v[46:47], v[46:47], v[50:51]
	s_nop 0
	v_div_scale_f32 v15, s[0:1], v47, v47, 1.0
	v_rcp_f32_e32 v17, v15
	s_nop 0
	v_fma_f32 v49, -v15, v17, 1.0
	v_fmac_f32_e32 v17, v49, v17
	v_div_scale_f32 v49, vcc, 1.0, v47, 1.0
	v_mul_f32_e32 v50, v49, v17
	v_fma_f32 v51, -v15, v50, v49
	v_fmac_f32_e32 v50, v51, v17
	v_fma_f32 v15, -v15, v50, v49
	v_div_fmas_f32 v15, v15, v17, v50
	v_div_fixup_f32 v51, v15, v47, 1.0
	v_div_scale_f32 v15, s[0:1], v46, v46, 1.0
	v_rcp_f32_e32 v17, v15
	s_nop 0
	v_fma_f32 v49, -v15, v17, 1.0
	v_fmac_f32_e32 v17, v49, v17
	v_div_scale_f32 v49, vcc, 1.0, v46, 1.0
	v_mul_f32_e32 v50, v49, v17
	v_fma_f32 v54, -v15, v50, v49
	v_fmac_f32_e32 v50, v54, v17
	ds_bpermute_b32 v54, v60, v44
	v_fma_f32 v15, -v15, v50, v49
	v_div_fmas_f32 v15, v15, v17, v50
	v_div_fixup_f32 v50, v15, v46, 1.0
	v_pk_mul_f32 v[2:3], v[2:3], v[50:51]
	s_waitcnt lgkmcnt(0)
	v_pk_add_f32 v[44:45], v[44:45], v[54:55]
	ds_bpermute_b32 v54, v61, v44
	ds_bpermute_b32 v55, v65, v45
	s_waitcnt lgkmcnt(0)
	v_pk_add_f32 v[44:45], v[44:45], v[54:55]
	ds_bpermute_b32 v54, v62, v44
	ds_bpermute_b32 v55, v66, v45
	s_waitcnt lgkmcnt(0)
	v_pk_add_f32 v[44:45], v[44:45], v[54:55]
	ds_bpermute_b32 v54, v63, v44
	ds_bpermute_b32 v55, v67, v45
	s_waitcnt lgkmcnt(0)
	v_pk_add_f32 v[44:45], v[44:45], v[54:55]
	s_nop 0
	v_div_scale_f32 v15, s[0:1], v45, v45, 1.0
	v_rcp_f32_e32 v17, v15
	s_nop 0
	v_fma_f32 v49, -v15, v17, 1.0
	v_fmac_f32_e32 v17, v49, v17
	v_div_scale_f32 v49, vcc, 1.0, v45, 1.0
	v_mul_f32_e32 v54, v49, v17
	v_fma_f32 v55, -v15, v54, v49
	v_fmac_f32_e32 v54, v55, v17
	v_fma_f32 v15, -v15, v54, v49
	v_div_fmas_f32 v15, v15, v17, v54
	v_div_fixup_f32 v55, v15, v45, 1.0
	v_div_scale_f32 v15, s[0:1], v44, v44, 1.0
	v_rcp_f32_e32 v17, v15
	s_nop 0
	v_fma_f32 v49, -v15, v17, 1.0
	v_fmac_f32_e32 v17, v49, v17
	v_div_scale_f32 v49, vcc, 1.0, v44, 1.0
	v_mul_f32_e32 v54, v49, v17
	v_fma_f32 v56, -v15, v54, v49
	v_fmac_f32_e32 v54, v56, v17
	v_fma_f32 v15, -v15, v54, v49
	v_div_fmas_f32 v15, v15, v17, v54
	v_div_fixup_f32 v54, v15, v44, 1.0
	v_pk_mul_f32 v[4:5], v[4:5], v[54:55]
	ds_write_b128 v203, v[2:5]
	v_pk_mul_f32 v[2:3], v[6:7], v[50:51]
	v_pk_mul_f32 v[4:5], v[8:9], v[54:55]
	ds_write_b128 v203, v[2:5] offset:1024
	v_pk_mul_f32 v[2:3], v[10:11], v[50:51]
	v_pk_mul_f32 v[4:5], v[18:19], v[54:55]
	ds_write_b128 v203, v[2:5] offset:2048
	v_pk_mul_f32 v[2:3], v[20:21], v[50:51]
	v_pk_mul_f32 v[4:5], v[22:23], v[54:55]
	ds_write_b128 v203, v[2:5] offset:3072
	v_pk_mul_f32 v[2:3], v[24:25], v[50:51]
	v_pk_mul_f32 v[4:5], v[26:27], v[54:55]
	ds_write_b128 v203, v[2:5] offset:4096
	v_pk_mul_f32 v[2:3], v[28:29], v[50:51]
	v_pk_mul_f32 v[4:5], v[30:31], v[54:55]
	ds_write_b128 v203, v[2:5] offset:5120
	v_pk_mul_f32 v[2:3], v[32:33], v[50:51]
	v_pk_mul_f32 v[4:5], v[34:35], v[54:55]
	ds_write_b128 v203, v[2:5] offset:6144
	v_pk_mul_f32 v[2:3], v[36:37], v[50:51]
	v_pk_mul_f32 v[4:5], v[38:39], v[54:55]
	ds_write_b128 v203, v[2:5] offset:7168
	v_pk_mul_f32 v[2:3], v[40:41], v[50:51]
	v_pk_mul_f32 v[4:5], v[42:43], v[54:55]
	ds_write_b128 v203, v[2:5] offset:8192
	s_and_saveexec_b64 s[2:3], s[6:7]
	s_cbranch_execz .LBB0_136
	s_mov_b32 s4, 0x800000
	v_cmp_gt_f32_e32 vcc, s4, v46
	s_mov_b32 s5, 0x3f317217
	s_mov_b32 s10, 0x7f800000
	v_cndmask_b32_e64 v2, 0, 32, vcc
	v_ldexp_f32 v2, v46, v2
	v_log_f32_e32 v4, v2
	v_mov_b32_e32 v17, v157
	v_ashrrev_i32_e32 v49, 31, v48
	v_lshl_add_u64 v[2:3], v[48:49], 2, s[82:83]
	v_mul_f32_e32 v5, 0x3f317217, v4
	v_fma_f32 v5, v4, s5, -v5
	v_fmac_f32_e32 v5, 0x3377d1cf, v4
	v_fmac_f32_e32 v5, 0x3f317217, v4
	v_cmp_lt_f32_e64 s[0:1], |v4|, s10
	v_mov_b32_e32 v15, v157
	s_nop 0
	v_cndmask_b32_e64 v4, v4, v5, s[0:1]
	v_cndmask_b32_e32 v5, 0, v190, vcc
	v_sub_f32_e32 v4, v4, v5
	v_add_f32_e32 v1, v1, v4
	v_lshlrev_b64 v[4:5], v204, v[16:17]
	v_lshl_add_u64 v[4:5], v[4:5], 0, v[136:137]
	v_mad_u64_u32 v[6:7], s[0:1], v4, 48, v[2:3]
	v_cmp_gt_f32_e32 vcc, s4, v47
	v_mov_b32_e32 v4, v7
	v_mad_u64_u32 v[4:5], s[0:1], v5, 48, v[4:5]
	v_cndmask_b32_e64 v7, 0, 32, vcc
	v_ldexp_f32 v7, v47, v7
	v_log_f32_e32 v8, v7
	v_mov_b32_e32 v7, v4
	global_store_dword v[6:7], v1, off
	v_cndmask_b32_e32 v4, 0, v190, vcc
	v_mul_f32_e32 v1, 0x3f317217, v8
	v_fma_f32 v1, v8, s5, -v1
	v_fmac_f32_e32 v1, 0x3377d1cf, v8
	v_fmac_f32_e32 v1, 0x3f317217, v8
	v_cmp_lt_f32_e64 s[0:1], |v8|, s10
	v_cmp_gt_f32_e32 vcc, s4, v44
	s_nop 0
	v_cndmask_b32_e64 v1, v8, v1, s[0:1]
	v_sub_f32_e32 v1, v1, v4
	v_lshlrev_b64 v[4:5], v204, v[14:15]
	v_lshl_add_u64 v[4:5], v[4:5], 0, v[136:137]
	v_mad_u64_u32 v[6:7], s[0:1], v4, 48, v[2:3]
	v_mov_b32_e32 v4, v7
	v_cndmask_b32_e64 v7, 0, 32, vcc
	v_ldexp_f32 v7, v44, v7
	v_log_f32_e32 v8, v7
	v_mad_u64_u32 v[4:5], s[0:1], v5, 48, v[4:5]
	v_add_f32_e32 v1, v13, v1
	v_mov_b32_e32 v7, v4
	global_store_dword v[6:7], v1, off
	v_mul_f32_e32 v1, 0x3f317217, v8
	v_fma_f32 v1, v8, s5, -v1
	v_fmac_f32_e32 v1, 0x3377d1cf, v8
	v_fmac_f32_e32 v1, 0x3f317217, v8
	v_cmp_lt_f32_e64 s[0:1], |v8|, s10
	v_cndmask_b32_e32 v4, 0, v190, vcc
	v_mov_b32_e32 v13, v157
	v_cndmask_b32_e64 v1, v8, v1, s[0:1]
	v_sub_f32_e32 v1, v1, v4
	v_lshlrev_b64 v[4:5], v204, v[12:13]
	v_lshl_add_u64 v[4:5], v[4:5], 0, v[136:137]
	v_mad_u64_u32 v[6:7], s[0:1], v4, 48, v[2:3]
	v_cmp_gt_f32_e32 vcc, s4, v45
	v_mov_b32_e32 v4, v7
	v_mad_u64_u32 v[4:5], s[0:1], v5, 48, v[4:5]
	v_cndmask_b32_e64 v7, 0, 32, vcc
	v_ldexp_f32 v7, v45, v7
	v_log_f32_e32 v8, v7
	v_add_f32_e32 v1, v52, v1
	v_mov_b32_e32 v7, v4
	global_store_dword v[6:7], v1, off
	v_mul_f32_e32 v1, 0x3f317217, v8
	v_fma_f32 v1, v8, s5, -v1
	v_fmac_f32_e32 v1, 0x3377d1cf, v8
	v_fmac_f32_e32 v1, 0x3f317217, v8
	v_cmp_lt_f32_e64 s[0:1], |v8|, s10
	v_cndmask_b32_e32 v4, 0, v190, vcc
	s_nop 0
	v_cndmask_b32_e64 v1, v8, v1, s[0:1]
	v_sub_f32_e32 v1, v1, v4
	v_add_f32_e32 v4, v53, v1
	v_mov_b32_e32 v1, v157
	v_lshlrev_b64 v[0:1], v204, v[0:1]
	v_lshl_add_u64 v[0:1], v[0:1], 0, v[136:137]
	v_mad_u64_u32 v[2:3], s[0:1], v0, 48, v[2:3]
	v_mov_b32_e32 v0, v3
	v_mad_u64_u32 v[0:1], s[0:1], v1, 48, v[0:1]
	v_mov_b32_e32 v3, v0
	global_store_dword v[2:3], v4, off

; DEV f32x4 mfma16(bf16x8 a, bf16x8 b, f32x4 c) { return __builtin_amdgcn_mfma_f32_16x16x32_bf16(a, b, c, 0, 0, 0); }
; PHASE void att_b_phase(const u16* __restrict__ GB, const int* __restrict__ SEL, u16* __restrict__ OB, unsigned char* smem) {
;     ...
;   for (int bi = blockIdx.x; bi < T_ / 4; bi += gridDim.x) {
;     const int tok = bi * 4 + wid;
;     const int b = tok >> 14;
;     const size_t base = (size_t)b * S_;
;     const int* sel = SEL + (size_t)tok * 256;
;     bf16x8 qa[4];
;     {
;       const u16* qrow = GB + (size_t)tok * 2896 + (fr < 12 ? fr : 0) * 128;
; #pragma unroll
;       for (int ks = 0; ks < 4; ++ks) {
;         bf16x8 q = *(const bf16x8*)(qrow + ks * 32 + fq * 8);
;         if (fr >= 12) q = bf16x8{0, 0, 0, 0, 0, 0, 0, 0};
;         qa[ks] = q;
;       }
;     }
;     __syncthreads();
; #pragma unroll
;     for (int i = 0; i < 4; ++i) sl[lane + 64 * i] = sel[lane + 64 * i];
;     f32x4 sc[16];
;     float mx[4] = {-1e30f, -1e30f, -1e30f, -1e30f};
; #pragma unroll
;     for (int kt = 0; kt < 16; ++kt) {
;       int ki = sel[kt * 16 + fr];
;       bool valid = ki >= 0;
;       int kc = valid ? ki : 0;
;       const u16* krow = GB + (base + kc) * 2896 + 1536;
;       f32x4 acc = {0.f, 0.f, 0.f, 0.f};
; #pragma unroll
;       for (int ks = 0; ks < 4; ++ks) {
;         bf16x8 kb = *(const bf16x8*)(krow + ks * 32 + fq * 8);
;         acc = mfma16(qa[ks], kb, acc);
;       }
; #pragma unroll
;       for (int j = 0; j < 4; ++j) {
;         float v = valid ? acc[j] * scale : -1e30f;
;         acc[j] = v;
;         mx[j] = fmaxf(mx[j], v);
;       }
;       sc[kt] = acc;
;     }
.LBB0_428:
	v_lshl_add_u32 v116, s4, 2, v144
	v_ashrrev_i32_e32 v117, 31, v116
	v_lshlrev_b64 v[10:11], 10, v[116:117]
	v_mad_i64_i32 v[12:13], s[2:3], v116, s80, v[104:105]
	v_lshl_add_u64 v[10:11], s[78:79], 0, v[10:11]
	v_mov_b32_e32 v113, v157
	global_load_dwordx4 v[0:3], v[12:13], off
	global_load_dwordx4 v[4:7], v[12:13], off offset:64
	global_load_dwordx4 v[18:21], v[12:13], off offset:128
	global_load_dwordx4 v[22:25], v[12:13], off offset:192
	v_lshl_add_u64 v[12:13], v[10:11], 0, v[112:113]
	s_barrier
	global_load_dword v14, v[12:13], off
	global_load_dword v15, v[12:13], off offset:256
	v_ashrrev_i32_e32 v8, 14, v116
	v_mov_b32_e32 v115, v157
	v_ashrrev_i32_e32 v9, 31, v8
	v_lshl_add_u64 v[16:17], v[10:11], 0, v[114:115]
	v_lshlrev_b64 v[118:119], 14, v[8:9]
	s_waitcnt vmcnt(0)
	ds_write2st64_b32 v146, v14, v15 offset0:48 offset1:49
	global_load_dword v14, v[12:13], off offset:512
	s_nop 0
	global_load_dword v12, v[12:13], off offset:768
	v_cndmask_b32_e64 v15, v3, 0, s[6:7]
	global_load_dword v200, v[16:17], off
	global_load_dword v201, v[16:17], off offset:64
	global_load_dword v202, v[16:17], off offset:128
	global_load_dword v203, v[16:17], off offset:192
	global_load_dword v204, v[16:17], off offset:256
	global_load_dword v205, v[16:17], off offset:320
	global_load_dword v206, v[16:17], off offset:384
	global_load_dword v207, v[16:17], off offset:448
	global_load_dword v208, v[16:17], off offset:512
	global_load_dword v209, v[16:17], off offset:576
	global_load_dword v210, v[16:17], off offset:640
	global_load_dword v211, v[16:17], off offset:704
	global_load_dword v212, v[16:17], off offset:768
	global_load_dword v213, v[16:17], off offset:832
	global_load_dword v214, v[16:17], off offset:896
	global_load_dword v215, v[16:17], off offset:960
	v_cndmask_b32_e64 v13, v1, 0, s[6:7]
	s_waitcnt vmcnt(1)
	ds_write2st64_b32 v146, v14, v12 offset0:50 offset1:51
	v_cndmask_b32_e64 v14, v2, 0, s[6:7]
	s_waitcnt vmcnt(0)
	v_mov_b32_e32 v8, v200
	v_cmp_lt_i32_e32 vcc, -1, v8
	v_cndmask_b32_e64 v12, v0, 0, s[6:7]
	s_nop 0
	v_cndmask_b32_e32 v8, 0, v8, vcc
	v_ashrrev_i32_e32 v9, 31, v8
	v_lshl_add_u64 v[8:9], v[118:119], 0, v[8:9]
	v_mad_u64_u32 v[30:31], s[2:3], v8, s80, v[108:109]
	v_mad_i32_i24 v31, v9, s80, v31
	global_load_dwordx4 v[8:11], v[30:31], off offset:3072
	global_load_dwordx4 v[26:29], v[30:31], off offset:3136
	global_load_dwordx4 v[216:219], v[30:31], off offset:3200
	global_load_dwordx4 v[220:223], v[30:31], off offset:3264
	s_waitcnt vmcnt(3)
	v_mfma_f32_16x16x32_bf16 v[0:3], v[12:15], v[8:11], 0
	v_cndmask_b32_e64 v11, v7, 0, s[6:7]
	v_cndmask_b32_e64 v10, v6, 0, s[6:7]
	v_cndmask_b32_e64 v9, v5, 0, s[6:7]
	v_cndmask_b32_e64 v8, v4, 0, s[6:7]
	v_cndmask_b32_e64 v7, v21, 0, s[6:7]
	v_cndmask_b32_e64 v6, v20, 0, s[6:7]
	s_waitcnt vmcnt(2)
	v_mfma_f32_16x16x32_bf16 v[0:3], v[8:11], v[26:29], v[0:3]
	v_cndmask_b32_e64 v5, v19, 0, s[6:7]
	v_cndmask_b32_e64 v4, v18, 0, s[6:7]
	s_waitcnt vmcnt(1)
	s_nop 0
	v_mfma_f32_16x16x32_bf16 v[18:21], v[4:7], v[216:219], v[0:3]
	s_nop 1
	v_cndmask_b32_e64 v3, v25, 0, s[6:7]
	v_cndmask_b32_e64 v2, v24, 0, s[6:7]
	v_cndmask_b32_e64 v1, v23, 0, s[6:7]
	v_cndmask_b32_e64 v0, v22, 0, s[6:7]
	s_waitcnt vmcnt(0)
	s_nop 0
	v_mfma_f32_16x16x32_bf16 v[22:25], v[0:3], v[220:223], v[18:21]
	s_nop 7
	v_mul_f32_e32 v18, 0x3db504f3, v22
	v_cndmask_b32_e32 v21, v185, v18, vcc
	v_mul_f32_e32 v18, 0x3db504f3, v23
	v_cndmask_b32_e32 v20, v185, v18, vcc
	v_mul_f32_e32 v18, 0x3db504f3, v24
	v_cndmask_b32_e32 v19, v185, v18, vcc
	v_mul_f32_e32 v18, 0x3db504f3, v25
	v_cndmask_b32_e32 v18, v185, v18, vcc
	s_waitcnt vmcnt(0)
	v_mov_b32_e32 v22, v201
	v_cmp_lt_i32_e32 vcc, -1, v22
	s_nop 1
	v_cndmask_b32_e32 v22, 0, v22, vcc
	v_ashrrev_i32_e32 v23, 31, v22
	v_lshl_add_u64 v[22:23], v[118:119], 0, v[22:23]
	v_mad_u64_u32 v[30:31], s[2:3], v22, s80, v[108:109]
	v_mad_i32_i24 v31, v23, s80, v31
	global_load_dwordx4 v[22:25], v[30:31], off offset:3072
	global_load_dwordx4 v[26:29], v[30:31], off offset:3136
	global_load_dwordx4 v[216:219], v[30:31], off offset:3200
	global_load_dwordx4 v[220:223], v[30:31], off offset:3264
	s_mov_b32 s2, 0xf149f2ca
	s_waitcnt vmcnt(3)
	v_mfma_f32_16x16x32_bf16 v[22:25], v[12:15], v[22:25], 0
	s_waitcnt vmcnt(2)
	v_mfma_f32_16x16x32_bf16 v[22:25], v[8:11], v[26:29], v[22:25]
	s_waitcnt vmcnt(1)
	v_mfma_f32_16x16x32_bf16 v[22:25], v[4:7], v[216:219], v[22:25]
	s_waitcnt vmcnt(0)
	v_mfma_f32_16x16x32_bf16 v[22:25], v[0:3], v[220:223], v[22:25]
	s_nop 6
	v_mul_f32_e32 v22, 0x3db504f3, v22
	v_mul_f32_e32 v23, 0x3db504f3, v23
	v_mul_f32_e32 v24, 0x3db504f3, v24
	v_mul_f32_e32 v25, 0x3db504f3, v25
	v_cndmask_b32_e32 v22, v185, v22, vcc
	v_cndmask_b32_e32 v23, v185, v23, vcc
	v_cndmask_b32_e32 v24, v185, v24, vcc
	v_cndmask_b32_e32 v25, v185, v25, vcc
	v_max3_f32 v40, v21, s2, v22
	v_max3_f32 v41, v20, s2, v23
	v_max3_f32 v42, v19, s2, v24
	v_max3_f32 v43, v18, s2, v25
	s_waitcnt vmcnt(0)
	v_mov_b32_e32 v26, v202
	v_cmp_lt_i32_e32 vcc, -1, v26
	s_nop 1
	v_cndmask_b32_e32 v26, 0, v26, vcc
	v_ashrrev_i32_e32 v27, 31, v26
	v_lshl_add_u64 v[26:27], v[118:119], 0, v[26:27]
	v_mad_u64_u32 v[34:35], s[2:3], v26, s80, v[108:109]
	v_mad_i32_i24 v35, v27, s80, v35
	global_load_dwordx4 v[26:29], v[34:35], off offset:3072
	global_load_dwordx4 v[30:33], v[34:35], off offset:3136
	global_load_dwordx4 v[216:219], v[34:35], off offset:3200
	global_load_dwordx4 v[220:223], v[34:35], off offset:3264
	s_waitcnt vmcnt(3)
	v_mfma_f32_16x16x32_bf16 v[26:29], v[12:15], v[26:29], 0
	s_waitcnt vmcnt(2)
	v_mfma_f32_16x16x32_bf16 v[26:29], v[8:11], v[30:33], v[26:29]
	s_waitcnt vmcnt(1)
; DEV f32x4 mfma16(bf16x8 a, bf16x8 b, f32x4 c) { return __builtin_amdgcn_mfma_f32_16x16x32_bf16(a, b, c, 0, 0, 0); }
; PHASE void att_b_phase(const u16* __restrict__ GB, const int* __restrict__ SEL, u16* __restrict__ OB, unsigned char* smem) {
;     ...
;     for (int kt = 0; kt < 16; ++kt) {
;       int ki = sel[kt * 16 + fr];
;       bool valid = ki >= 0;
;       int kc = valid ? ki : 0;
;       const u16* krow = GB + (base + kc) * 2896 + 1536;
;       f32x4 acc = {0.f, 0.f, 0.f, 0.f};
; #pragma unroll
;       for (int ks = 0; ks < 4; ++ks) {
;         bf16x8 kb = *(const bf16x8*)(krow + ks * 32 + fq * 8);
;         acc = mfma16(qa[ks], kb, acc);
;       }
; #pragma unroll
;       for (int j = 0; j < 4; ++j) {
;         float v = valid ? acc[j] * scale : -1e30f;
;         acc[j] = v;
;         mx[j] = fmaxf(mx[j], v);
;       }
;       sc[kt] = acc;
;     }
	v_mfma_f32_16x16x32_bf16 v[26:29], v[4:7], v[216:219], v[26:29]
	s_waitcnt vmcnt(0)
	v_mfma_f32_16x16x32_bf16 v[30:33], v[0:3], v[220:223], v[26:29]
	s_nop 7
	v_mul_f32_e32 v26, 0x3db504f3, v30
	v_cndmask_b32_e32 v29, v185, v26, vcc
	v_mul_f32_e32 v26, 0x3db504f3, v31
	v_cndmask_b32_e32 v28, v185, v26, vcc
	v_mul_f32_e32 v26, 0x3db504f3, v32
	v_cndmask_b32_e32 v27, v185, v26, vcc
	v_mul_f32_e32 v26, 0x3db504f3, v33
	v_cndmask_b32_e32 v26, v185, v26, vcc
	s_waitcnt vmcnt(0)
	v_mov_b32_e32 v30, v203
	v_cmp_lt_i32_e32 vcc, -1, v30
	s_nop 1
	v_cndmask_b32_e32 v30, 0, v30, vcc
	v_ashrrev_i32_e32 v31, 31, v30
	v_lshl_add_u64 v[30:31], v[118:119], 0, v[30:31]
	v_mad_u64_u32 v[38:39], s[2:3], v30, s80, v[108:109]
	v_mad_i32_i24 v39, v31, s80, v39
	global_load_dwordx4 v[30:33], v[38:39], off offset:3072
	global_load_dwordx4 v[34:37], v[38:39], off offset:3136
	global_load_dwordx4 v[216:219], v[38:39], off offset:3200
	global_load_dwordx4 v[220:223], v[38:39], off offset:3264
	s_waitcnt vmcnt(3)
	v_mfma_f32_16x16x32_bf16 v[30:33], v[12:15], v[30:33], 0
	s_waitcnt vmcnt(2)
	v_mfma_f32_16x16x32_bf16 v[30:33], v[8:11], v[34:37], v[30:33]
	s_waitcnt vmcnt(1)
	v_mfma_f32_16x16x32_bf16 v[30:33], v[4:7], v[216:219], v[30:33]
	s_waitcnt vmcnt(0)
	v_mfma_f32_16x16x32_bf16 v[30:33], v[0:3], v[220:223], v[30:33]
	s_nop 6
	v_mul_f32_e32 v30, 0x3db504f3, v30
	v_mul_f32_e32 v31, 0x3db504f3, v31
	v_mul_f32_e32 v32, 0x3db504f3, v32
	v_mul_f32_e32 v33, 0x3db504f3, v33
	v_cndmask_b32_e32 v30, v185, v30, vcc
	v_cndmask_b32_e32 v31, v185, v31, vcc
	v_cndmask_b32_e32 v32, v185, v32, vcc
	v_cndmask_b32_e32 v33, v185, v33, vcc
	v_max3_f32 v50, v42, v27, v32
	v_max3_f32 v51, v43, v26, v33
	v_max3_f32 v48, v40, v29, v30
	v_max3_f32 v49, v41, v28, v31
	s_waitcnt vmcnt(0)
	v_mov_b32_e32 v34, v204
	v_cmp_lt_i32_e32 vcc, -1, v34
	s_nop 1
	v_cndmask_b32_e32 v34, 0, v34, vcc
	v_ashrrev_i32_e32 v35, 31, v34
	v_lshl_add_u64 v[34:35], v[118:119], 0, v[34:35]
	v_mad_u64_u32 v[42:43], s[2:3], v34, s80, v[108:109]
	v_mad_i32_i24 v43, v35, s80, v43
	global_load_dwordx4 v[34:37], v[42:43], off offset:3072
	global_load_dwordx4 v[38:41], v[42:43], off offset:3136
	global_load_dwordx4 v[216:219], v[42:43], off offset:3200
	global_load_dwordx4 v[220:223], v[42:43], off offset:3264
	s_waitcnt vmcnt(3)
	v_mfma_f32_16x16x32_bf16 v[34:37], v[12:15], v[34:37], 0
	s_waitcnt vmcnt(2)
	v_mfma_f32_16x16x32_bf16 v[34:37], v[8:11], v[38:41], v[34:37]
	s_waitcnt vmcnt(1)
	v_mfma_f32_16x16x32_bf16 v[34:37], v[4:7], v[216:219], v[34:37]
	s_waitcnt vmcnt(0)
	v_mfma_f32_16x16x32_bf16 v[38:41], v[0:3], v[220:223], v[34:37]
	s_nop 7
	v_mul_f32_e32 v34, 0x3db504f3, v38
	v_cndmask_b32_e32 v37, v185, v34, vcc
	v_mul_f32_e32 v34, 0x3db504f3, v39
	v_cndmask_b32_e32 v36, v185, v34, vcc
	v_mul_f32_e32 v34, 0x3db504f3, v40
	v_cndmask_b32_e32 v35, v185, v34, vcc
	v_mul_f32_e32 v34, 0x3db504f3, v41
	v_cndmask_b32_e32 v34, v185, v34, vcc
	s_waitcnt vmcnt(0)
	v_mov_b32_e32 v38, v205
	v_cmp_lt_i32_e32 vcc, -1, v38
	s_nop 1
	v_cndmask_b32_e32 v38, 0, v38, vcc
	v_ashrrev_i32_e32 v39, 31, v38
	v_lshl_add_u64 v[38:39], v[118:119], 0, v[38:39]
	v_mad_u64_u32 v[46:47], s[2:3], v38, s80, v[108:109]
	v_mad_i32_i24 v47, v39, s80, v47
	global_load_dwordx4 v[38:41], v[46:47], off offset:3072
	global_load_dwordx4 v[42:45], v[46:47], off offset:3136
	global_load_dwordx4 v[216:219], v[46:47], off offset:3200
	global_load_dwordx4 v[220:223], v[46:47], off offset:3264
	s_waitcnt vmcnt(3)
	v_mfma_f32_16x16x32_bf16 v[38:41], v[12:15], v[38:41], 0
	s_waitcnt vmcnt(2)
	v_mfma_f32_16x16x32_bf16 v[38:41], v[8:11], v[42:45], v[38:41]
	s_waitcnt vmcnt(1)
	v_mfma_f32_16x16x32_bf16 v[38:41], v[4:7], v[216:219], v[38:41]
	s_waitcnt vmcnt(0)
	v_mfma_f32_16x16x32_bf16 v[38:41], v[0:3], v[220:223], v[38:41]
	s_nop 6
	v_mul_f32_e32 v38, 0x3db504f3, v38
	v_mul_f32_e32 v39, 0x3db504f3, v39
	v_mul_f32_e32 v40, 0x3db504f3, v40
	v_mul_f32_e32 v41, 0x3db504f3, v41
	v_cndmask_b32_e32 v38, v185, v38, vcc
	v_cndmask_b32_e32 v39, v185, v39, vcc
	v_cndmask_b32_e32 v40, v185, v40, vcc
	v_cndmask_b32_e32 v41, v185, v41, vcc
	v_max3_f32 v58, v50, v35, v40
	v_max3_f32 v59, v51, v34, v41
	v_max3_f32 v56, v48, v37, v38
	v_max3_f32 v57, v49, v36, v39
	s_waitcnt vmcnt(0)
	v_mov_b32_e32 v42, v206
	v_cmp_lt_i32_e32 vcc, -1, v42
	s_nop 1
	v_cndmask_b32_e32 v42, 0, v42, vcc
	v_ashrrev_i32_e32 v43, 31, v42
	v_lshl_add_u64 v[42:43], v[118:119], 0, v[42:43]
	v_mad_u64_u32 v[50:51], s[2:3], v42, s80, v[108:109]
	v_mad_i32_i24 v51, v43, s80, v51
	global_load_dwordx4 v[42:45], v[50:51], off offset:3072
	global_load_dwordx4 v[46:49], v[50:51], off offset:3136
	global_load_dwordx4 v[216:219], v[50:51], off offset:3200
	global_load_dwordx4 v[220:223], v[50:51], off offset:3264
	s_waitcnt vmcnt(3)
	v_mfma_f32_16x16x32_bf16 v[42:45], v[12:15], v[42:45], 0
	s_waitcnt vmcnt(2)
	v_mfma_f32_16x16x32_bf16 v[42:45], v[8:11], v[46:49], v[42:45]
	s_waitcnt vmcnt(1)
	v_mfma_f32_16x16x32_bf16 v[42:45], v[4:7], v[216:219], v[42:45]
	s_waitcnt vmcnt(0)
	v_mfma_f32_16x16x32_bf16 v[46:49], v[0:3], v[220:223], v[42:45]
	s_nop 7
	v_mul_f32_e32 v42, 0x3db504f3, v46
	v_cndmask_b32_e32 v45, v185, v42, vcc
	v_mul_f32_e32 v42, 0x3db504f3, v47
	v_cndmask_b32_e32 v44, v185, v42, vcc
	v_mul_f32_e32 v42, 0x3db504f3, v48
	v_cndmask_b32_e32 v43, v185, v42, vcc
	v_mul_f32_e32 v42, 0x3db504f3, v49
	v_cndmask_b32_e32 v42, v185, v42, vcc
	s_waitcnt vmcnt(0)
; DEV f32x4 mfma16(bf16x8 a, bf16x8 b, f32x4 c) { return __builtin_amdgcn_mfma_f32_16x16x32_bf16(a, b, c, 0, 0, 0); }
; PHASE void att_b_phase(const u16* __restrict__ GB, const int* __restrict__ SEL, u16* __restrict__ OB, unsigned char* smem) {
;     ...
;     for (int kt = 0; kt < 16; ++kt) {
;       int ki = sel[kt * 16 + fr];
;       bool valid = ki >= 0;
;       int kc = valid ? ki : 0;
;       const u16* krow = GB + (base + kc) * 2896 + 1536;
;       f32x4 acc = {0.f, 0.f, 0.f, 0.f};
; #pragma unroll
;       for (int ks = 0; ks < 4; ++ks) {
;         bf16x8 kb = *(const bf16x8*)(krow + ks * 32 + fq * 8);
;         acc = mfma16(qa[ks], kb, acc);
;       }
; #pragma unroll
;       for (int j = 0; j < 4; ++j) {
;         float v = valid ? acc[j] * scale : -1e30f;
;         acc[j] = v;
;         mx[j] = fmaxf(mx[j], v);
;       }
;       sc[kt] = acc;
	v_mov_b32_e32 v46, v207
	v_cmp_lt_i32_e32 vcc, -1, v46
	s_nop 1
	v_cndmask_b32_e32 v46, 0, v46, vcc
	v_ashrrev_i32_e32 v47, 31, v46
	v_lshl_add_u64 v[46:47], v[118:119], 0, v[46:47]
	v_mad_u64_u32 v[54:55], s[2:3], v46, s80, v[108:109]
	v_mad_i32_i24 v55, v47, s80, v55
	global_load_dwordx4 v[46:49], v[54:55], off offset:3072
	global_load_dwordx4 v[50:53], v[54:55], off offset:3136
	global_load_dwordx4 v[216:219], v[54:55], off offset:3200
	global_load_dwordx4 v[220:223], v[54:55], off offset:3264
	s_waitcnt vmcnt(3)
	v_mfma_f32_16x16x32_bf16 v[46:49], v[12:15], v[46:49], 0
	s_waitcnt vmcnt(2)
	v_mfma_f32_16x16x32_bf16 v[46:49], v[8:11], v[50:53], v[46:49]
	s_waitcnt vmcnt(1)
	v_mfma_f32_16x16x32_bf16 v[46:49], v[4:7], v[216:219], v[46:49]
	s_waitcnt vmcnt(0)
	v_mfma_f32_16x16x32_bf16 v[46:49], v[0:3], v[220:223], v[46:49]
	s_nop 6
	v_mul_f32_e32 v46, 0x3db504f3, v46
	v_mul_f32_e32 v47, 0x3db504f3, v47
	v_mul_f32_e32 v48, 0x3db504f3, v48
	v_mul_f32_e32 v49, 0x3db504f3, v49
	v_cndmask_b32_e32 v46, v185, v46, vcc
	v_cndmask_b32_e32 v47, v185, v47, vcc
	v_cndmask_b32_e32 v48, v185, v48, vcc
	v_cndmask_b32_e32 v49, v185, v49, vcc
	v_max3_f32 v66, v58, v43, v48
	v_max3_f32 v67, v59, v42, v49
	v_max3_f32 v64, v56, v45, v46
	v_max3_f32 v65, v57, v44, v47
	s_waitcnt vmcnt(0)
	v_mov_b32_e32 v50, v208
	v_cmp_lt_i32_e32 vcc, -1, v50
	s_nop 1
	v_cndmask_b32_e32 v50, 0, v50, vcc
	v_ashrrev_i32_e32 v51, 31, v50
	v_lshl_add_u64 v[50:51], v[118:119], 0, v[50:51]
	v_mad_u64_u32 v[58:59], s[2:3], v50, s80, v[108:109]
	v_mad_i32_i24 v59, v51, s80, v59
	global_load_dwordx4 v[50:53], v[58:59], off offset:3072
	global_load_dwordx4 v[54:57], v[58:59], off offset:3136
	global_load_dwordx4 v[216:219], v[58:59], off offset:3200
	global_load_dwordx4 v[220:223], v[58:59], off offset:3264
	s_waitcnt vmcnt(3)
	v_mfma_f32_16x16x32_bf16 v[50:53], v[12:15], v[50:53], 0
	s_waitcnt vmcnt(2)
	v_mfma_f32_16x16x32_bf16 v[50:53], v[8:11], v[54:57], v[50:53]
	s_waitcnt vmcnt(1)
	v_mfma_f32_16x16x32_bf16 v[50:53], v[4:7], v[216:219], v[50:53]
	s_waitcnt vmcnt(0)
	v_mfma_f32_16x16x32_bf16 v[54:57], v[0:3], v[220:223], v[50:53]
	s_nop 7
	v_mul_f32_e32 v50, 0x3db504f3, v54
	v_cndmask_b32_e32 v53, v185, v50, vcc
	v_mul_f32_e32 v50, 0x3db504f3, v55
	v_cndmask_b32_e32 v52, v185, v50, vcc
	v_mul_f32_e32 v50, 0x3db504f3, v56
	v_cndmask_b32_e32 v51, v185, v50, vcc
	v_mul_f32_e32 v50, 0x3db504f3, v57
	v_cndmask_b32_e32 v50, v185, v50, vcc
	s_waitcnt vmcnt(0)
	v_mov_b32_e32 v54, v209
	v_cmp_lt_i32_e32 vcc, -1, v54
	s_nop 1
	v_cndmask_b32_e32 v54, 0, v54, vcc
	v_ashrrev_i32_e32 v55, 31, v54
	v_lshl_add_u64 v[54:55], v[118:119], 0, v[54:55]
	v_mad_u64_u32 v[62:63], s[2:3], v54, s80, v[108:109]
	v_mad_i32_i24 v63, v55, s80, v63
	global_load_dwordx4 v[54:57], v[62:63], off offset:3072
	global_load_dwordx4 v[58:61], v[62:63], off offset:3136
	global_load_dwordx4 v[216:219], v[62:63], off offset:3200
	global_load_dwordx4 v[220:223], v[62:63], off offset:3264
	s_waitcnt vmcnt(3)
	v_mfma_f32_16x16x32_bf16 v[54:57], v[12:15], v[54:57], 0
	s_waitcnt vmcnt(2)
	v_mfma_f32_16x16x32_bf16 v[54:57], v[8:11], v[58:61], v[54:57]
	s_waitcnt vmcnt(1)
	v_mfma_f32_16x16x32_bf16 v[54:57], v[4:7], v[216:219], v[54:57]
	s_waitcnt vmcnt(0)
	v_mfma_f32_16x16x32_bf16 v[54:57], v[0:3], v[220:223], v[54:57]
	s_nop 6
	v_mul_f32_e32 v54, 0x3db504f3, v54
	v_mul_f32_e32 v55, 0x3db504f3, v55
	v_mul_f32_e32 v56, 0x3db504f3, v56
	v_mul_f32_e32 v57, 0x3db504f3, v57
	v_cndmask_b32_e32 v54, v185, v54, vcc
	v_cndmask_b32_e32 v55, v185, v55, vcc
	v_cndmask_b32_e32 v56, v185, v56, vcc
	v_cndmask_b32_e32 v57, v185, v57, vcc
	v_max3_f32 v74, v66, v51, v56
	v_max3_f32 v76, v67, v50, v57
	v_max3_f32 v72, v64, v53, v54
	v_max3_f32 v73, v65, v52, v55
	s_waitcnt vmcnt(0)
	v_mov_b32_e32 v58, v210
	v_cmp_lt_i32_e32 vcc, -1, v58
	s_nop 1
	v_cndmask_b32_e32 v58, 0, v58, vcc
	v_ashrrev_i32_e32 v59, 31, v58
	v_lshl_add_u64 v[58:59], v[118:119], 0, v[58:59]
	v_mad_u64_u32 v[66:67], s[2:3], v58, s80, v[108:109]
	v_mad_i32_i24 v67, v59, s80, v67
	global_load_dwordx4 v[58:61], v[66:67], off offset:3072
	global_load_dwordx4 v[62:65], v[66:67], off offset:3136
	global_load_dwordx4 v[216:219], v[66:67], off offset:3200
	global_load_dwordx4 v[220:223], v[66:67], off offset:3264
	s_waitcnt vmcnt(3)
	v_mfma_f32_16x16x32_bf16 v[58:61], v[12:15], v[58:61], 0
	s_waitcnt vmcnt(2)
	v_mfma_f32_16x16x32_bf16 v[58:61], v[8:11], v[62:65], v[58:61]
	s_waitcnt vmcnt(1)
	v_mfma_f32_16x16x32_bf16 v[58:61], v[4:7], v[216:219], v[58:61]
	s_waitcnt vmcnt(0)
	v_mfma_f32_16x16x32_bf16 v[62:65], v[0:3], v[220:223], v[58:61]
	s_nop 7
	v_mul_f32_e32 v58, 0x3db504f3, v62
	v_cndmask_b32_e32 v61, v185, v58, vcc
	v_mul_f32_e32 v58, 0x3db504f3, v63
	v_cndmask_b32_e32 v60, v185, v58, vcc
	v_mul_f32_e32 v58, 0x3db504f3, v64
	v_cndmask_b32_e32 v59, v185, v58, vcc
	v_mul_f32_e32 v58, 0x3db504f3, v65
	v_cndmask_b32_e32 v58, v185, v58, vcc
	s_waitcnt vmcnt(0)
	v_mov_b32_e32 v62, v211
	v_cmp_lt_i32_e32 vcc, -1, v62
	s_nop 1
	v_cndmask_b32_e32 v62, 0, v62, vcc
	v_ashrrev_i32_e32 v63, 31, v62
	v_lshl_add_u64 v[62:63], v[118:119], 0, v[62:63]
	v_mad_u64_u32 v[70:71], s[2:3], v62, s80, v[108:109]
	v_mad_i32_i24 v71, v63, s80, v71
	global_load_dwordx4 v[62:65], v[70:71], off offset:3072
	global_load_dwordx4 v[66:69], v[70:71], off offset:3136
	global_load_dwordx4 v[216:219], v[70:71], off offset:3200
	global_load_dwordx4 v[220:223], v[70:71], off offset:3264
	s_waitcnt vmcnt(3)
	v_mfma_f32_16x16x32_bf16 v[62:65], v[12:15], v[62:65], 0
	s_waitcnt vmcnt(2)
	v_mfma_f32_16x16x32_bf16 v[62:65], v[8:11], v[66:69], v[62:65]
	s_waitcnt vmcnt(1)
	v_mfma_f32_16x16x32_bf16 v[62:65], v[4:7], v[216:219], v[62:65]
	s_waitcnt vmcnt(0)
; DEV f32x4 mfma16(bf16x8 a, bf16x8 b, f32x4 c) { return __builtin_amdgcn_mfma_f32_16x16x32_bf16(a, b, c, 0, 0, 0); }
; PHASE void att_b_phase(const u16* __restrict__ GB, const int* __restrict__ SEL, u16* __restrict__ OB, unsigned char* smem) {
;     ...
;     for (int kt = 0; kt < 16; ++kt) {
;       int ki = sel[kt * 16 + fr];
;       bool valid = ki >= 0;
;       int kc = valid ? ki : 0;
;       const u16* krow = GB + (base + kc) * 2896 + 1536;
;       f32x4 acc = {0.f, 0.f, 0.f, 0.f};
; #pragma unroll
;       for (int ks = 0; ks < 4; ++ks) {
;         bf16x8 kb = *(const bf16x8*)(krow + ks * 32 + fq * 8);
;         acc = mfma16(qa[ks], kb, acc);
;       }
; #pragma unroll
;       for (int j = 0; j < 4; ++j) {
;         float v = valid ? acc[j] * scale : -1e30f;
;         acc[j] = v;
;         mx[j] = fmaxf(mx[j], v);
;       }
;       sc[kt] = acc;
;     }
;     float l[4] = {0.f, 0.f, 0.f, 0.f}, inv[4];
; #pragma unroll
;     for (int j = 0; j < 4; ++j) mx[j] = grp16_max(mx[j]);
	v_mfma_f32_16x16x32_bf16 v[64:67], v[0:3], v[220:223], v[62:65]
	s_nop 6
	v_mul_f32_e32 v62, 0x3db504f3, v64
	v_mul_f32_e32 v63, 0x3db504f3, v65
	v_mul_f32_e32 v66, 0x3db504f3, v66
	v_mul_f32_e32 v67, 0x3db504f3, v67
	v_cndmask_b32_e32 v62, v185, v62, vcc
	v_cndmask_b32_e32 v63, v185, v63, vcc
	v_cndmask_b32_e32 v66, v185, v66, vcc
	v_cndmask_b32_e32 v67, v185, v67, vcc
	v_max3_f32 v64, v72, v61, v62
	v_max3_f32 v65, v73, v60, v63
	v_max3_f32 v75, v74, v59, v66
	v_max3_f32 v76, v76, v58, v67
	s_waitcnt vmcnt(0)
	v_mov_b32_e32 v68, v212
	v_cmp_lt_i32_e32 vcc, -1, v68
	s_nop 1
	v_cndmask_b32_e32 v68, 0, v68, vcc
	v_ashrrev_i32_e32 v69, 31, v68
	v_lshl_add_u64 v[68:69], v[118:119], 0, v[68:69]
	v_mad_u64_u32 v[72:73], s[2:3], v68, s80, v[108:109]
	v_mad_i32_i24 v73, v69, s80, v73
	global_load_dwordx4 v[68:71], v[72:73], off offset:3072
	global_load_dwordx4 v[78:81], v[72:73], off offset:3136
	global_load_dwordx4 v[216:219], v[72:73], off offset:3200
	global_load_dwordx4 v[220:223], v[72:73], off offset:3264
	s_waitcnt vmcnt(3)
	v_mfma_f32_16x16x32_bf16 v[68:71], v[12:15], v[68:71], 0
	s_waitcnt vmcnt(2)
	v_mfma_f32_16x16x32_bf16 v[68:71], v[8:11], v[78:81], v[68:71]
	s_waitcnt vmcnt(1)
	v_mfma_f32_16x16x32_bf16 v[68:71], v[4:7], v[216:219], v[68:71]
	s_nop 0
	s_waitcnt vmcnt(0)
	v_mfma_f32_16x16x32_bf16 v[78:81], v[0:3], v[220:223], v[68:71]
	s_nop 7
	v_mul_f32_e32 v68, 0x3db504f3, v78
	v_cndmask_b32_e32 v71, v185, v68, vcc
	v_mul_f32_e32 v68, 0x3db504f3, v79
	v_cndmask_b32_e32 v70, v185, v68, vcc
	v_mul_f32_e32 v68, 0x3db504f3, v80
	v_cndmask_b32_e32 v69, v185, v68, vcc
	v_mul_f32_e32 v68, 0x3db504f3, v81
	v_cndmask_b32_e32 v68, v185, v68, vcc
	s_waitcnt vmcnt(0)
	v_mov_b32_e32 v72, v213
	v_cmp_lt_i32_e32 vcc, -1, v72
	s_nop 1
	v_cndmask_b32_e32 v72, 0, v72, vcc
	v_ashrrev_i32_e32 v73, 31, v72
	v_lshl_add_u64 v[72:73], v[118:119], 0, v[72:73]
	v_mad_u64_u32 v[86:87], s[2:3], v72, s80, v[108:109]
	v_mad_i32_i24 v87, v73, s80, v87
	global_load_dwordx4 v[78:81], v[86:87], off offset:3072
	global_load_dwordx4 v[82:85], v[86:87], off offset:3136
	global_load_dwordx4 v[216:219], v[86:87], off offset:3200
	global_load_dwordx4 v[220:223], v[86:87], off offset:3264
	s_waitcnt vmcnt(3)
	v_mfma_f32_16x16x32_bf16 v[78:81], v[12:15], v[78:81], 0
	s_waitcnt vmcnt(2)
	v_mfma_f32_16x16x32_bf16 v[78:81], v[8:11], v[82:85], v[78:81]
	s_waitcnt vmcnt(1)
	v_mfma_f32_16x16x32_bf16 v[78:81], v[4:7], v[216:219], v[78:81]
	s_waitcnt vmcnt(0)
	v_mfma_f32_16x16x32_bf16 v[78:81], v[0:3], v[220:223], v[78:81]
	s_nop 7
	v_mul_f32_e32 v74, 0x3db504f3, v80
	v_cndmask_b32_e32 v74, v185, v74, vcc
	v_max3_f32 v80, v75, v69, v74
	v_mul_f32_e32 v75, 0x3db504f3, v81
	v_cndmask_b32_e32 v75, v185, v75, vcc
	v_max3_f32 v81, v76, v68, v75
	v_mul_f32_e32 v72, 0x3db504f3, v78
	v_mul_f32_e32 v73, 0x3db504f3, v79
	v_cndmask_b32_e32 v72, v185, v72, vcc
	v_cndmask_b32_e32 v73, v185, v73, vcc
	v_max3_f32 v64, v64, v71, v72
	v_max3_f32 v65, v65, v70, v73
	s_waitcnt vmcnt(1)
	v_mov_b32_e32 v76, v214
	v_cmp_lt_i32_e32 vcc, -1, v76
	s_nop 1
	v_cndmask_b32_e32 v76, 0, v76, vcc
	v_ashrrev_i32_e32 v77, 31, v76
	v_lshl_add_u64 v[76:77], v[118:119], 0, v[76:77]
	v_mad_u64_u32 v[86:87], s[2:3], v76, s80, v[108:109]
	v_mad_i32_i24 v87, v77, s80, v87
	global_load_dwordx4 v[76:79], v[86:87], off offset:3072
	global_load_dwordx4 v[82:85], v[86:87], off offset:3136
	global_load_dwordx4 v[216:219], v[86:87], off offset:3200
	global_load_dwordx4 v[220:223], v[86:87], off offset:3264
	s_waitcnt vmcnt(3)
	v_mfma_f32_16x16x32_bf16 v[76:79], v[12:15], v[76:79], 0
	s_waitcnt vmcnt(2)
	v_mfma_f32_16x16x32_bf16 v[76:79], v[8:11], v[82:85], v[76:79]
	s_waitcnt vmcnt(1)
	v_mfma_f32_16x16x32_bf16 v[76:79], v[4:7], v[216:219], v[76:79]
	s_waitcnt vmcnt(0)
	v_mfma_f32_16x16x32_bf16 v[82:85], v[0:3], v[220:223], v[76:79]
	s_nop 7
	v_mul_f32_e32 v76, 0x3db504f3, v82
	v_cndmask_b32_e32 v79, v185, v76, vcc
	v_mul_f32_e32 v76, 0x3db504f3, v83
	v_cndmask_b32_e32 v78, v185, v76, vcc
	v_mul_f32_e32 v76, 0x3db504f3, v84
	v_cndmask_b32_e32 v77, v185, v76, vcc
	v_mul_f32_e32 v76, 0x3db504f3, v85
	v_cndmask_b32_e32 v76, v185, v76, vcc
	v_mov_b32_e32 v16, v215
	v_cmp_lt_i32_e32 vcc, -1, v16
	s_nop 1
	v_cndmask_b32_e32 v16, 0, v16, vcc
	v_ashrrev_i32_e32 v17, 31, v16
	v_lshl_add_u64 v[16:17], v[118:119], 0, v[16:17]
	v_mad_u64_u32 v[86:87], s[2:3], v16, s80, v[108:109]
	v_mad_i32_i24 v87, v17, s80, v87
	global_load_dwordx4 v[82:85], v[86:87], off offset:3072
	s_waitcnt vmcnt(0)
	v_mfma_f32_16x16x32_bf16 v[12:15], v[12:15], v[82:85], 0
	global_load_dwordx4 v[82:85], v[86:87], off offset:3136
	s_waitcnt vmcnt(0)
	v_mfma_f32_16x16x32_bf16 v[8:11], v[8:11], v[82:85], v[12:15]
	s_nop 4
	global_load_dwordx4 v[12:15], v[86:87], off offset:3200
	s_waitcnt vmcnt(0)
	v_mfma_f32_16x16x32_bf16 v[4:7], v[4:7], v[12:15], v[8:11]
	s_nop 2
	global_load_dwordx4 v[8:11], v[86:87], off offset:3264
	s_waitcnt vmcnt(0)
	v_mfma_f32_16x16x32_bf16 v[0:3], v[0:3], v[8:11], v[4:7]
	s_nop 2
	v_mov_b32_e32 v4, v184
	s_nop 3
	v_mul_f32_e32 v0, 0x3db504f3, v0
	v_cndmask_b32_e32 v82, v185, v0, vcc
	v_lshlrev_b32_e32 v4, 2, v4
	v_max3_f32 v0, v64, v79, v82
	v_xor_b32_e32 v4, 32, v4
	ds_bpermute_b32 v4, v4, v0
	v_mul_f32_e32 v2, 0x3db504f3, v2
	v_cndmask_b32_e32 v84, v185, v2, vcc
	v_mul_f32_e32 v3, 0x3db504f3, v3
	v_max3_f32 v2, v80, v77, v84
	s_waitcnt lgkmcnt(0)
	v_max_f32_e32 v4, v4, v4
	v_max_f32_e32 v0, v0, v4
	v_mov_b32_e32 v4, v184
	v_cndmask_b32_e32 v80, v185, v3, vcc
	v_lshlrev_b32_e32 v4, 2, v4
	v_xor_b32_e32 v4, 16, v4
	ds_bpermute_b32 v4, v4, v0
	v_max3_f32 v3, v81, v76, v80
	v_mul_f32_e32 v1, 0x3db504f3, v1
	v_cndmask_b32_e32 v83, v185, v1, vcc
	v_max3_f32 v1, v65, v78, v83
	s_waitcnt lgkmcnt(0)
; PHASE void att_b_phase(const u16* __restrict__ GB, const int* __restrict__ SEL, u16* __restrict__ OB, unsigned char* smem) {
;     ...
;     float l[4] = {0.f, 0.f, 0.f, 0.f}, inv[4];
; #pragma unroll
;     for (int j = 0; j < 4; ++j) mx[j] = grp16_max(mx[j]);
; #pragma unroll
;     for (int kt = 0; kt < 16; ++kt)
; #pragma unroll
;       for (int j = 0; j < 4; ++j) {
;         float e = __expf(sc[kt][j] - mx[j]);
;         sc[kt][j] = e;
;         l[j] += e;
;       }
	v_max_f32_e32 v4, v4, v4
	v_max_f32_e32 v0, v0, v4
	v_mov_b32_e32 v4, v184
	s_nop 0
	v_lshlrev_b32_e32 v4, 2, v4
	v_xor_b32_e32 v4, 8, v4
	ds_bpermute_b32 v4, v4, v0
	s_waitcnt lgkmcnt(0)
	v_max_f32_e32 v4, v4, v4
	v_max_f32_e32 v0, v0, v4
	v_mov_b32_e32 v4, v184
	s_nop 0
	v_lshlrev_b32_e32 v4, 2, v4
	v_xor_b32_e32 v4, 4, v4
	ds_bpermute_b32 v4, v4, v0
	s_waitcnt lgkmcnt(0)
	v_max_f32_e32 v4, v4, v4
	v_max_f32_e32 v81, v0, v4
	v_mov_b32_e32 v0, v184
	v_sub_f32_e32 v4, v22, v81
	v_lshlrev_b32_e32 v0, 2, v0
	v_xor_b32_e32 v0, 32, v0
	ds_bpermute_b32 v0, v0, v1
	v_mul_f32_e32 v4, 0x3fb8aa3b, v4
	v_sub_f32_e32 v8, v29, v81
	v_exp_f32_e32 v4, v4
	v_mul_f32_e32 v8, 0x3fb8aa3b, v8
	s_waitcnt lgkmcnt(0)
	v_max_f32_e32 v0, v0, v0
	v_max_f32_e32 v0, v1, v0
	v_mov_b32_e32 v1, v184
	v_sub_f32_e32 v12, v30, v81
	v_lshlrev_b32_e32 v1, 2, v1
	v_xor_b32_e32 v1, 16, v1
	ds_bpermute_b32 v1, v1, v0
	v_exp_f32_e32 v8, v8
	v_mul_f32_e32 v12, 0x3fb8aa3b, v12
	v_sub_f32_e32 v16, v37, v81
	v_exp_f32_e32 v12, v12
	s_waitcnt lgkmcnt(0)
	v_max_f32_e32 v1, v1, v1
	v_max_f32_e32 v0, v0, v1
	v_mov_b32_e32 v1, v184
	v_mul_f32_e32 v16, 0x3fb8aa3b, v16
	v_lshlrev_b32_e32 v1, 2, v1
	v_xor_b32_e32 v1, 8, v1
	ds_bpermute_b32 v1, v1, v0
	v_exp_f32_e32 v16, v16
	s_waitcnt lgkmcnt(0)
	v_max_f32_e32 v1, v1, v1
	v_max_f32_e32 v0, v0, v1
	v_mov_b32_e32 v1, v184
	s_nop 0
	v_lshlrev_b32_e32 v1, 2, v1
	v_xor_b32_e32 v1, 4, v1
	ds_bpermute_b32 v1, v1, v0
	s_waitcnt lgkmcnt(0)
	v_max_f32_e32 v1, v1, v1
	v_max_f32_e32 v85, v0, v1
	v_mov_b32_e32 v0, v184
	v_mov_b32_e32 v1, v184
	v_lshlrev_b32_e32 v0, 2, v0
	v_xor_b32_e32 v0, 32, v0
	ds_bpermute_b32 v0, v0, v2
	v_sub_f32_e32 v5, v23, v85
	v_lshlrev_b32_e32 v1, 2, v1
	v_xor_b32_e32 v1, 16, v1
	s_waitcnt lgkmcnt(0)
	v_max_f32_e32 v0, v0, v0
	v_max_f32_e32 v0, v2, v0
	ds_bpermute_b32 v1, v1, v0
	v_mul_f32_e32 v5, 0x3fb8aa3b, v5
	v_sub_f32_e32 v9, v28, v85
	v_exp_f32_e32 v5, v5
	v_mul_f32_e32 v9, 0x3fb8aa3b, v9
	s_waitcnt lgkmcnt(0)
	v_max_f32_e32 v1, v1, v1
	v_max_f32_e32 v0, v0, v1
	v_mov_b32_e32 v1, v184
	v_sub_f32_e32 v13, v31, v85
	v_lshlrev_b32_e32 v1, 2, v1
	v_xor_b32_e32 v1, 8, v1
	ds_bpermute_b32 v1, v1, v0
	v_exp_f32_e32 v9, v9
	v_mul_f32_e32 v13, 0x3fb8aa3b, v13
	v_sub_f32_e32 v17, v36, v85
	v_exp_f32_e32 v13, v13
	s_waitcnt lgkmcnt(0)
	v_max_f32_e32 v1, v1, v1
	v_max_f32_e32 v0, v0, v1
	v_mov_b32_e32 v1, v184
	v_mul_f32_e32 v17, 0x3fb8aa3b, v17
	v_lshlrev_b32_e32 v1, 2, v1
	v_xor_b32_e32 v1, 4, v1
	ds_bpermute_b32 v1, v1, v0
	v_exp_f32_e32 v17, v17
	v_sub_f32_e32 v28, v46, v81
	v_sub_f32_e32 v29, v47, v85
	v_mul_f32_e32 v28, 0x3fb8aa3b, v28
	s_waitcnt lgkmcnt(0)
	v_max_f32_e32 v1, v1, v1
	v_max_f32_e32 v88, v0, v1
	v_mov_b32_e32 v0, v184
	v_mov_b32_e32 v1, v184
	v_lshlrev_b32_e32 v0, 2, v0
	v_xor_b32_e32 v0, 32, v0
	ds_bpermute_b32 v0, v0, v3
	v_sub_f32_e32 v2, v19, v88
	v_lshlrev_b32_e32 v1, 2, v1
	v_xor_b32_e32 v1, 16, v1
	s_waitcnt lgkmcnt(0)
	v_max_f32_e32 v0, v0, v0
	v_max_f32_e32 v0, v3, v0
	ds_bpermute_b32 v1, v1, v0
	v_sub_f32_e32 v6, v24, v88
	v_sub_f32_e32 v10, v27, v88
	v_sub_f32_e32 v24, v45, v81
	v_mul_f32_e32 v2, 0x3fb8aa3b, v2
	s_waitcnt lgkmcnt(0)
	v_max_f32_e32 v1, v1, v1
	v_max_f32_e32 v0, v0, v1
	v_mov_b32_e32 v1, v184
	v_mul_f32_e32 v24, 0x3fb8aa3b, v24
	v_lshlrev_b32_e32 v1, 2, v1
	v_xor_b32_e32 v1, 8, v1
	ds_bpermute_b32 v1, v1, v0
	v_sub_f32_e32 v46, v66, v88
	v_mov_b32_e32 v66, v184
	v_exp_f32_e32 v2, v2
	v_mul_f32_e32 v6, 0x3fb8aa3b, v6
	s_waitcnt lgkmcnt(0)
	v_max_f32_e32 v1, v1, v1
	v_max_f32_e32 v0, v0, v1
	v_mov_b32_e32 v1, v184
	v_sub_f32_e32 v14, v32, v88
	v_lshlrev_b32_e32 v1, 2, v1
	v_xor_b32_e32 v1, 4, v1
	ds_bpermute_b32 v1, v1, v0
	v_exp_f32_e32 v24, v24
	v_mul_f32_e32 v29, 0x3fb8aa3b, v29
	v_sub_f32_e32 v32, v53, v81
	s_waitcnt lgkmcnt(0)
	v_max_f32_e32 v1, v1, v1
	v_max_f32_e32 v89, v0, v1
	v_sub_f32_e32 v0, v21, v81
	v_sub_f32_e32 v1, v20, v85
	v_mul_f32_e32 v0, 0x3fb8aa3b, v0
	v_mul_f32_e32 v1, 0x3fb8aa3b, v1
	v_exp_f32_e32 v0, v0
	v_exp_f32_e32 v1, v1
	v_sub_f32_e32 v20, v38, v81
	v_sub_f32_e32 v21, v39, v85
	v_sub_f32_e32 v3, v18, v89
	v_sub_f32_e32 v7, v25, v89
	v_sub_f32_e32 v11, v26, v89
	v_mul_f32_e32 v20, 0x3fb8aa3b, v20
	v_mul_f32_e32 v21, 0x3fb8aa3b, v21
	v_sub_f32_e32 v25, v44, v85
	v_sub_f32_e32 v26, v43, v88
	v_sub_f32_e32 v27, v42, v89
	v_pk_add_f32 v[42:43], v[0:1], 0 op_sel_hi:[1,0]
	v_mul_f32_e32 v3, 0x3fb8aa3b, v3
	v_exp_f32_e32 v20, v20
	v_exp_f32_e32 v21, v21
	v_mul_f32_e32 v25, 0x3fb8aa3b, v25
	v_pk_add_f32 v[42:43], v[4:5], v[42:43]
	v_exp_f32_e32 v3, v3
	v_mul_f32_e32 v7, 0x3fb8aa3b, v7
	v_sub_f32_e32 v15, v33, v89
	v_exp_f32_e32 v25, v25
	v_sub_f32_e32 v33, v52, v85
	v_pk_add_f32 v[42:43], v[8:9], v[42:43]
	v_exp_f32_e32 v6, v6
	v_exp_f32_e32 v7, v7
	v_mul_f32_e32 v10, 0x3fb8aa3b, v10
	v_mul_f32_e32 v11, 0x3fb8aa3b, v11
	v_exp_f32_e32 v28, v28
	v_exp_f32_e32 v29, v29
	v_mul_f32_e32 v32, 0x3fb8aa3b, v32
	v_mul_f32_e32 v33, 0x3fb8aa3b, v33
	v_sub_f32_e32 v36, v54, v81
	v_sub_f32_e32 v37, v55, v85
	v_pk_add_f32 v[42:43], v[12:13], v[42:43]
	v_lshlrev_b32_e32 v66, 2, v66
	v_exp_f32_e32 v10, v10
	v_exp_f32_e32 v11, v11
	v_mul_f32_e32 v14, 0x3fb8aa3b, v14
	v_mul_f32_e32 v15, 0x3fb8aa3b, v15
	v_sub_f32_e32 v18, v35, v88
	v_sub_f32_e32 v19, v34, v89
	v_sub_f32_e32 v22, v40, v88
	v_sub_f32_e32 v23, v41, v89
	v_exp_f32_e32 v32, v32
	v_exp_f32_e32 v33, v33
	v_sub_f32_e32 v34, v51, v88
	v_mul_f32_e32 v36, 0x3fb8aa3b, v36
	v_mul_f32_e32 v37, 0x3fb8aa3b, v37
	v_sub_f32_e32 v40, v61, v81
	v_sub_f32_e32 v41, v60, v85
	v_pk_add_f32 v[42:43], v[16:17], v[42:43]
	v_sub_f32_e32 v51, v68, v89
	v_xor_b32_e32 v68, 32, v66
	v_mov_b32_e32 v66, v184
	v_exp_f32_e32 v14, v14
	v_exp_f32_e32 v15, v15
; PHASE void att_b_phase(const u16* __restrict__ GB, const int* __restrict__ SEL, u16* __restrict__ OB, unsigned char* smem) {
;     ...
; #pragma unroll
;     for (int kt = 0; kt < 16; ++kt)
; #pragma unroll
;       for (int j = 0; j < 4; ++j) {
;         float e = __expf(sc[kt][j] - mx[j]);
;         sc[kt][j] = e;
;         l[j] += e;
;       }
; #pragma unroll
;     for (int j = 0; j < 4; ++j) {
;       l[j] = grp16_sum(l[j]);
;       inv[j] = 1.f / l[j];
;     }
;     if (fq < 3) {
	v_mul_f32_e32 v18, 0x3fb8aa3b, v18
	v_mul_f32_e32 v19, 0x3fb8aa3b, v19
	v_exp_f32_e32 v36, v36
	v_exp_f32_e32 v37, v37
	v_mul_f32_e32 v40, 0x3fb8aa3b, v40
	v_mul_f32_e32 v41, 0x3fb8aa3b, v41
	v_pk_add_f32 v[42:43], v[20:21], v[42:43]
	v_exp_f32_e32 v18, v18
	v_exp_f32_e32 v19, v19
	v_mul_f32_e32 v22, 0x3fb8aa3b, v22
	v_mul_f32_e32 v23, 0x3fb8aa3b, v23
	v_exp_f32_e32 v40, v40
	v_exp_f32_e32 v41, v41
	v_pk_add_f32 v[42:43], v[24:25], v[42:43]
	v_pk_add_f32 v[44:45], v[2:3], 0 op_sel_hi:[1,0]
	v_lshlrev_b32_e32 v66, 2, v66
	v_exp_f32_e32 v22, v22
	v_exp_f32_e32 v23, v23
	v_mul_f32_e32 v26, 0x3fb8aa3b, v26
	v_mul_f32_e32 v27, 0x3fb8aa3b, v27
	v_sub_f32_e32 v30, v48, v88
	v_sub_f32_e32 v31, v49, v89
	v_pk_add_f32 v[42:43], v[28:29], v[42:43]
	v_pk_add_f32 v[44:45], v[6:7], v[44:45]
	v_sub_f32_e32 v49, v70, v85
	v_xor_b32_e32 v70, 16, v66
	v_mov_b32_e32 v66, v184
	v_exp_f32_e32 v26, v26
	v_exp_f32_e32 v27, v27
	v_mul_f32_e32 v30, 0x3fb8aa3b, v30
	v_mul_f32_e32 v31, 0x3fb8aa3b, v31
	v_sub_f32_e32 v35, v50, v89
	v_pk_add_f32 v[42:43], v[32:33], v[42:43]
	v_pk_add_f32 v[44:45], v[10:11], v[44:45]
	v_exp_f32_e32 v30, v30
	v_exp_f32_e32 v31, v31
	v_mul_f32_e32 v34, 0x3fb8aa3b, v34
	v_mul_f32_e32 v35, 0x3fb8aa3b, v35
	v_sub_f32_e32 v38, v56, v88
	v_sub_f32_e32 v39, v57, v89
	v_pk_add_f32 v[42:43], v[36:37], v[42:43]
	v_pk_add_f32 v[44:45], v[14:15], v[44:45]
	v_lshlrev_b32_e32 v66, 2, v66
	v_exp_f32_e32 v34, v34
	v_exp_f32_e32 v35, v35
	v_mul_f32_e32 v38, 0x3fb8aa3b, v38
	v_mul_f32_e32 v39, 0x3fb8aa3b, v39
	v_pk_add_f32 v[86:87], v[40:41], v[42:43]
	v_sub_f32_e32 v42, v59, v88
	v_sub_f32_e32 v43, v58, v89
	v_pk_add_f32 v[44:45], v[18:19], v[44:45]
	v_sub_f32_e32 v48, v71, v81
	v_xor_b32_e32 v71, 8, v66
	v_mov_b32_e32 v66, v184
	v_exp_f32_e32 v38, v38
	v_exp_f32_e32 v39, v39
	v_mul_f32_e32 v42, 0x3fb8aa3b, v42
	v_mul_f32_e32 v43, 0x3fb8aa3b, v43
	v_pk_add_f32 v[44:45], v[22:23], v[44:45]
	v_exp_f32_e32 v42, v42
	v_exp_f32_e32 v43, v43
	v_pk_add_f32 v[44:45], v[26:27], v[44:45]
	v_lshlrev_b32_e32 v66, 2, v66
	v_pk_add_f32 v[44:45], v[30:31], v[44:45]
	v_sub_f32_e32 v52, v72, v81
	v_xor_b32_e32 v72, 4, v66
	v_mov_b32_e32 v66, v184
	v_pk_add_f32 v[44:45], v[34:35], v[44:45]
	v_sub_f32_e32 v50, v69, v88
	v_pk_add_f32 v[44:45], v[38:39], v[44:45]
	v_lshlrev_b32_e32 v66, 2, v66
	v_pk_add_f32 v[64:65], v[42:43], v[44:45]
	v_sub_f32_e32 v44, v62, v81
	v_sub_f32_e32 v45, v63, v85
	v_xor_b32_e32 v69, 32, v66
	v_mov_b32_e32 v66, v184
	v_mul_f32_e32 v44, 0x3fb8aa3b, v44
	v_mul_f32_e32 v45, 0x3fb8aa3b, v45
	v_exp_f32_e32 v44, v44
	v_exp_f32_e32 v45, v45
	v_mul_f32_e32 v48, 0x3fb8aa3b, v48
	v_mul_f32_e32 v49, 0x3fb8aa3b, v49
	v_sub_f32_e32 v53, v73, v85
	v_lshlrev_b32_e32 v66, 2, v66
	v_exp_f32_e32 v48, v48
	v_exp_f32_e32 v49, v49
	v_mul_f32_e32 v52, 0x3fb8aa3b, v52
	v_mul_f32_e32 v53, 0x3fb8aa3b, v53
	v_sub_f32_e32 v56, v79, v81
	v_sub_f32_e32 v57, v78, v85
	v_xor_b32_e32 v73, 16, v66
	v_mov_b32_e32 v66, v184
	v_exp_f32_e32 v52, v52
	v_exp_f32_e32 v53, v53
	v_mul_f32_e32 v56, 0x3fb8aa3b, v56
	v_mul_f32_e32 v57, 0x3fb8aa3b, v57
	v_sub_f32_e32 v60, v82, v81
	v_sub_f32_e32 v61, v83, v85
	v_exp_f32_e32 v56, v56
	v_exp_f32_e32 v57, v57
	v_mul_f32_e32 v60, 0x3fb8aa3b, v60
	v_mul_f32_e32 v61, 0x3fb8aa3b, v61
	v_lshlrev_b32_e32 v66, 2, v66
	v_sub_f32_e32 v47, v67, v89
	v_sub_f32_e32 v54, v74, v88
	v_exp_f32_e32 v60, v60
	v_exp_f32_e32 v61, v61
	v_xor_b32_e32 v74, 8, v66
	v_pk_add_f32 v[66:67], v[44:45], v[86:87]
	v_mul_f32_e32 v46, 0x3fb8aa3b, v46
	v_pk_add_f32 v[66:67], v[48:49], v[66:67]
	v_mul_f32_e32 v47, 0x3fb8aa3b, v47
	v_pk_add_f32 v[66:67], v[52:53], v[66:67]
	v_exp_f32_e32 v46, v46
	v_pk_add_f32 v[66:67], v[56:57], v[66:67]
	v_exp_f32_e32 v47, v47
	v_pk_add_f32 v[66:67], v[60:61], v[66:67]
	ds_bpermute_b32 v68, v68, v66
	ds_bpermute_b32 v69, v69, v67
	v_mul_f32_e32 v50, 0x3fb8aa3b, v50
	v_mul_f32_e32 v51, 0x3fb8aa3b, v51
	v_sub_f32_e32 v55, v75, v89
	v_exp_f32_e32 v50, v50
	s_waitcnt lgkmcnt(0)
	v_pk_add_f32 v[66:67], v[66:67], v[68:69]
	ds_bpermute_b32 v68, v70, v66
	ds_bpermute_b32 v69, v73, v67
	v_mov_b32_e32 v70, v184
	v_exp_f32_e32 v51, v51
	v_mul_f32_e32 v54, 0x3fb8aa3b, v54
	v_mul_f32_e32 v55, 0x3fb8aa3b, v55
	s_waitcnt lgkmcnt(0)
	v_pk_add_f32 v[66:67], v[66:67], v[68:69]
	ds_bpermute_b32 v68, v71, v66
	ds_bpermute_b32 v69, v74, v67
	v_mov_b32_e32 v71, v184
	v_sub_f32_e32 v58, v77, v88
	v_sub_f32_e32 v59, v76, v89
	v_exp_f32_e32 v54, v54
	s_waitcnt lgkmcnt(0)
	v_pk_add_f32 v[66:67], v[66:67], v[68:69]
	v_mov_b32_e32 v69, v184
	ds_bpermute_b32 v68, v72, v66
	v_lshlrev_b32_e32 v71, 2, v71
	v_xor_b32_e32 v72, 16, v71
	v_mov_b32_e32 v71, v184
	v_exp_f32_e32 v55, v55
	v_lshlrev_b32_e32 v71, 2, v71
	v_mul_f32_e32 v58, 0x3fb8aa3b, v58
	v_mul_f32_e32 v59, 0x3fb8aa3b, v59
	v_sub_f32_e32 v62, v84, v88
	v_sub_f32_e32 v63, v80, v89
	v_xor_b32_e32 v73, 8, v71
	v_mov_b32_e32 v71, v184
	v_exp_f32_e32 v58, v58
	v_exp_f32_e32 v59, v59
	v_mul_f32_e32 v62, 0x3fb8aa3b, v62
	v_mul_f32_e32 v63, 0x3fb8aa3b, v63
	v_exp_f32_e32 v62, v62
	v_exp_f32_e32 v63, v63
	v_lshlrev_b32_e32 v71, 2, v71
	v_pk_add_f32 v[64:65], v[46:47], v[64:65]
	v_xor_b32_e32 v74, 4, v71
	v_mov_b32_e32 v71, v184
	v_pk_add_f32 v[64:65], v[50:51], v[64:65]
	v_lshlrev_b32_e32 v70, 2, v70
	v_pk_add_f32 v[64:65], v[54:55], v[64:65]
	v_lshlrev_b32_e32 v71, 2, v71
	v_pk_add_f32 v[64:65], v[58:59], v[64:65]
	v_xor_b32_e32 v70, 32, v70
	v_xor_b32_e32 v71, 32, v71
	v_pk_add_f32 v[64:65], v[62:63], v[64:65]
	ds_bpermute_b32 v70, v70, v64
	ds_bpermute_b32 v71, v71, v65
	v_mov_b32_e32 v75, v184
	v_mov_b32_e32 v76, v184
	v_lshlrev_b32_e32 v75, 2, v75
	v_xor_b32_e32 v75, 16, v75
	s_waitcnt lgkmcnt(0)
	v_pk_add_f32 v[64:65], v[64:65], v[70:71]
	ds_bpermute_b32 v70, v72, v64
	ds_bpermute_b32 v71, v75, v65
	v_lshlrev_b32_e32 v69, 2, v69
	v_lshlrev_b32_e32 v76, 2, v76
	v_xor_b32_e32 v76, 8, v76
	s_waitcnt lgkmcnt(0)
	v_pk_add_f32 v[64:65], v[64:65], v[70:71]
	ds_bpermute_b32 v70, v73, v64
	ds_bpermute_b32 v71, v76, v65
	v_xor_b32_e32 v69, 4, v69
	ds_bpermute_b32 v69, v69, v67
	s_waitcnt lgkmcnt(1)
	v_pk_add_f32 v[64:65], v[64:65], v[70:71]
	v_mov_b32_e32 v71, v184
	ds_bpermute_b32 v70, v74, v64
	v_lshlrev_b32_e32 v71, 2, v71
	v_xor_b32_e32 v71, 4, v71
	ds_bpermute_b32 v71, v71, v65
	s_and_saveexec_b64 s[2:3], s[8:9]
	s_cbranch_execz .LBB0_430
; PHASE void att_b_phase(const u16* __restrict__ GB, const int* __restrict__ SEL, u16* __restrict__ OB, unsigned char* smem) {
;     ...
; #pragma unroll
;     for (int j = 0; j < 4; ++j) {
;       l[j] = grp16_sum(l[j]);
;       inv[j] = 1.f / l[j];
;     }
;     if (fq < 3) {
; #pragma unroll
;       for (int kt = 0; kt < 16; ++kt) {
;         f32x4 pv = {sc[kt][0] * inv[0], sc[kt][1] * inv[1], sc[kt][2] * inv[2], sc[kt][3] * inv[3]};
;         *(f32x4*)(Pl + (kt * 16 + fr) * 12 + fq * 4) = pv;
;       }
;     }
	s_waitcnt lgkmcnt(2)
	v_pk_add_f32 v[66:67], v[66:67], v[68:69]
	s_waitcnt lgkmcnt(0)
	v_pk_add_f32 v[64:65], v[64:65], v[70:71]
	v_div_scale_f32 v68, s[10:11], v67, v67, 1.0
	v_rcp_f32_e32 v69, v68
	s_nop 0
	v_fma_f32 v72, -v68, v69, 1.0
	v_fmac_f32_e32 v69, v72, v69
	v_div_scale_f32 v72, vcc, 1.0, v67, 1.0
	v_mul_f32_e32 v73, v72, v69
	v_fma_f32 v74, -v68, v73, v72
	v_fmac_f32_e32 v73, v74, v69
	v_fma_f32 v68, -v68, v73, v72
	v_div_fmas_f32 v68, v68, v69, v73
	v_div_fixup_f32 v67, v68, v67, 1.0
	v_div_scale_f32 v68, s[10:11], v66, v66, 1.0
	v_rcp_f32_e32 v69, v68
	s_nop 0
	v_fma_f32 v72, -v68, v69, 1.0
	v_fmac_f32_e32 v69, v72, v69
	v_div_scale_f32 v72, vcc, 1.0, v66, 1.0
	v_mul_f32_e32 v73, v72, v69
	v_fma_f32 v74, -v68, v73, v72
	v_fmac_f32_e32 v73, v74, v69
	v_fma_f32 v68, -v68, v73, v72
	v_div_fmas_f32 v68, v68, v69, v73
	v_div_fixup_f32 v66, v68, v66, 1.0
	v_div_scale_f32 v68, s[10:11], v65, v65, 1.0
	v_rcp_f32_e32 v69, v68
	v_pk_mul_f32 v[0:1], v[0:1], v[66:67]
	v_fma_f32 v70, -v68, v69, 1.0
	v_fmac_f32_e32 v69, v70, v69
	v_div_scale_f32 v70, vcc, 1.0, v65, 1.0
	v_mul_f32_e32 v71, v70, v69
	v_fma_f32 v72, -v68, v71, v70
	v_fmac_f32_e32 v71, v72, v69
	v_fma_f32 v68, -v68, v71, v70
	v_div_fmas_f32 v68, v68, v69, v71
	v_div_fixup_f32 v65, v68, v65, 1.0
	v_div_scale_f32 v68, s[10:11], v64, v64, 1.0
	v_rcp_f32_e32 v69, v68
	s_nop 0
	v_fma_f32 v70, -v68, v69, 1.0
	v_fmac_f32_e32 v69, v70, v69
	v_div_scale_f32 v70, vcc, 1.0, v64, 1.0
	v_mul_f32_e32 v71, v70, v69
	v_fma_f32 v72, -v68, v71, v70
	v_fmac_f32_e32 v71, v72, v69
	v_fma_f32 v68, -v68, v71, v70
	v_div_fmas_f32 v68, v68, v69, v71
	v_div_fixup_f32 v64, v68, v64, 1.0
	v_pk_mul_f32 v[2:3], v[2:3], v[64:65]
	ds_write_b128 v148, v[0:3]
	v_pk_mul_f32 v[0:1], v[4:5], v[66:67]
	v_pk_mul_f32 v[2:3], v[6:7], v[64:65]
	ds_write_b128 v148, v[0:3] offset:768
	v_pk_mul_f32 v[0:1], v[8:9], v[66:67]
	v_pk_mul_f32 v[2:3], v[10:11], v[64:65]
	ds_write_b128 v148, v[0:3] offset:1536
	v_pk_mul_f32 v[0:1], v[12:13], v[66:67]
	v_pk_mul_f32 v[2:3], v[14:15], v[64:65]
	ds_write_b128 v148, v[0:3] offset:2304
	v_pk_mul_f32 v[0:1], v[16:17], v[66:67]
	v_pk_mul_f32 v[2:3], v[18:19], v[64:65]
	ds_write_b128 v148, v[0:3] offset:3072
	v_pk_mul_f32 v[0:1], v[20:21], v[66:67]
	v_pk_mul_f32 v[2:3], v[22:23], v[64:65]
	ds_write_b128 v148, v[0:3] offset:3840
	v_pk_mul_f32 v[0:1], v[24:25], v[66:67]
	v_pk_mul_f32 v[2:3], v[26:27], v[64:65]
	ds_write_b128 v148, v[0:3] offset:4608
	v_pk_mul_f32 v[0:1], v[28:29], v[66:67]
	v_pk_mul_f32 v[2:3], v[30:31], v[64:65]
	ds_write_b128 v148, v[0:3] offset:5376
	v_pk_mul_f32 v[0:1], v[32:33], v[66:67]
	v_pk_mul_f32 v[2:3], v[34:35], v[64:65]
	ds_write_b128 v148, v[0:3] offset:6144
	v_pk_mul_f32 v[0:1], v[36:37], v[66:67]
	v_pk_mul_f32 v[2:3], v[38:39], v[64:65]
	ds_write_b128 v148, v[0:3] offset:6912
	v_pk_mul_f32 v[0:1], v[40:41], v[66:67]
	v_pk_mul_f32 v[2:3], v[42:43], v[64:65]
	ds_write_b128 v148, v[0:3] offset:7680
	v_pk_mul_f32 v[0:1], v[44:45], v[66:67]
	v_pk_mul_f32 v[2:3], v[46:47], v[64:65]
	ds_write_b128 v148, v[0:3] offset:8448
	v_pk_mul_f32 v[0:1], v[48:49], v[66:67]
	v_pk_mul_f32 v[2:3], v[50:51], v[64:65]
	ds_write_b128 v148, v[0:3] offset:9216
	v_pk_mul_f32 v[0:1], v[52:53], v[66:67]
	v_pk_mul_f32 v[2:3], v[54:55], v[64:65]
	ds_write_b128 v148, v[0:3] offset:9984
	v_pk_mul_f32 v[0:1], v[56:57], v[66:67]
	v_pk_mul_f32 v[2:3], v[58:59], v[64:65]
	ds_write_b128 v148, v[0:3] offset:10752
	v_pk_mul_f32 v[0:1], v[60:61], v[66:67]
	v_pk_mul_f32 v[2:3], v[62:63], v[64:65]
	ds_write_b128 v148, v[0:3] offset:11520
